# lora2 trip loop: exact wait counts at loop top (no wait for previous trip's G stores)
# speedup vs baseline: 1.0018x; 1.0018x over previous
.LBB0_453:
	s_sub_i32 s2, s54, s56
	s_lshr_b32 s2, s2, 3
	s_add_i32 s2, s2, s56
	s_cmp_lt_i32 s54, s56
	s_cselect_b32 s24, s54, s2
	s_cselect_b32 s10, 0, s58
	s_cselect_b32 s60, 8, s59
	s_lshl_b32 s2, s24, 3
	v_and_or_b32 v56, s2, -16, v226
	v_cmp_gt_i32_e32 vcc, s71, v56
	v_mov_b32_e32 v0, 0xff
	v_mov_b32_e32 v1, 0x1fff
	v_cndmask_b32_e32 v0, v0, v1, vcc
	v_and_b32_e32 v1, v0, v56
	v_cmp_eq_u32_e64 s[38:39], 0, v1
	v_cmp_eq_u32_e64 s[36:37], v1, v0
	v_mov_b64_e32 v[0:1], s[40:41]
	v_mad_i64_i32 v[0:1], s[4:5], v56, s17, v[0:1]
	v_mov_b32_e32 v2, 0xffffd200
	v_cndmask_b32_e64 v3, -1, 0, s[38:39]
	v_cndmask_b32_e64 v2, v2, 0, s[38:39]
	v_lshl_add_u64 v[34:35], v[0:1], 0, v[166:167]
	v_lshl_add_u64 v[8:9], v[0:1], 0, v[2:3]
	v_mov_b32_e32 v2, 0x2e00
	v_add_co_u32_e32 v36, vcc, s79, v34
	v_cndmask_b32_e64 v208, v2, 0, s[36:37]
	s_nop 0
	v_addc_co_u32_e32 v37, vcc, 0, v35, vcc
	v_lshl_add_u64 v[32:33], v[0:1], 0, v[208:209]
	global_load_dwordx4 v[0:3], v[36:37], off offset:2560
	v_lshl_add_u64 v[40:41], v[8:9], 0, v[166:167]
	v_add_co_u32_e32 v38, vcc, s79, v40
	s_mov_b64 s[8:9], 0x2a00
	s_nop 0
	v_addc_co_u32_e32 v39, vcc, 0, v41, vcc
	v_lshl_add_u64 v[24:25], v[34:35], 0, s[8:9]
	v_lshl_add_u64 v[8:9], v[40:41], 0, s[8:9]
	s_mov_b64 s[12:13], 0x2b00
	v_lshl_add_u64 v[28:29], v[34:35], 0, s[12:13]
	s_lshl_b32 s2, s24, 9
	s_and_b32 s2, s2, 0x200
	v_ashrrev_i32_e32 v57, 31, v56
	v_mov_b32_e32 v197, v209
	s_waitcnt vmcnt(0)
	v_lshlrev_b32_e32 v18, 16, v0
	v_and_b32_e32 v19, 0xffff0000, v0
	v_lshlrev_b32_e32 v20, 16, v1
	v_and_b32_e32 v21, 0xffff0000, v1
	v_lshlrev_b32_e32 v4, 16, v2
	v_and_b32_e32 v5, 0xffff0000, v2
	v_lshlrev_b32_e32 v6, 16, v3
	v_and_b32_e32 v7, 0xffff0000, v3
	global_load_dwordx4 v[0:3], v[38:39], off offset:2560
	s_waitcnt vmcnt(0)
	v_cndmask_b32_e64 v3, v3, 0, s[38:39]
	v_cndmask_b32_e64 v2, v2, 0, s[38:39]
	v_cndmask_b32_e64 v1, v1, 0, s[38:39]
	v_cndmask_b32_e64 v0, v0, 0, s[38:39]
	v_lshlrev_b32_e32 v22, 16, v0
	v_and_b32_e32 v23, 0xffff0000, v0
	v_lshlrev_b32_e32 v26, 16, v1
	v_and_b32_e32 v27, 0xffff0000, v1
	v_lshlrev_b32_e32 v14, 16, v2
	v_and_b32_e32 v16, 0xffff0000, v2
	v_lshlrev_b32_e32 v15, 16, v3
	v_and_b32_e32 v17, 0xffff0000, v3
	global_load_dwordx4 v[0:3], v[172:173], off offset:16
	global_load_dwordx4 v[10:13], v[172:173], off
	v_sub_f32_e32 v23, v23, v19
	v_sub_f32_e32 v22, v22, v18
	v_sub_f32_e32 v27, v27, v21
	v_sub_f32_e32 v26, v26, v20
	v_sub_f32_e32 v17, v17, v7
	s_waitcnt vmcnt(0)
	v_pk_fma_f32 v[10:11], v[10:11], v[22:23], v[18:19]
	s_nop 0
	v_add_f32_e32 v10, v10, v10
	v_add_f32_e32 v11, v11, v11
	v_mul_f32_e32 v10, 0x3fb8aa3b, v10
	v_mul_f32_e32 v11, 0x3fb8aa3b, v11
	v_exp_f32_e32 v10, v10
	v_exp_f32_e32 v11, v11
	v_pk_fma_f32 v[12:13], v[12:13], v[26:27], v[20:21]
	v_pk_add_f32 v[10:11], v[10:11], 1.0 op_sel_hi:[1,0]
	s_nop 0
	v_div_scale_f32 v18, s[4:5], v11, v11, 2.0
	v_rcp_f32_e32 v19, v18
	v_add_f32_e32 v12, v12, v12
	v_add_f32_e32 v13, v13, v13
	v_mul_f32_e32 v12, 0x3fb8aa3b, v12
	v_fma_f32 v20, -v18, v19, 1.0
	v_fmac_f32_e32 v19, v20, v19
	v_div_scale_f32 v20, vcc, 2.0, v11, 2.0
	v_mul_f32_e32 v21, v20, v19
	v_fma_f32 v22, -v18, v21, v20
	v_fmac_f32_e32 v21, v22, v19
	v_fma_f32 v18, -v18, v21, v20
	v_div_fmas_f32 v18, v18, v19, v21
	v_div_fixup_f32 v11, v18, v11, 2.0
	v_div_scale_f32 v18, s[4:5], v10, v10, 2.0
	v_rcp_f32_e32 v19, v18
	v_mul_f32_e32 v13, 0x3fb8aa3b, v13
	v_exp_f32_e32 v12, v12
	v_exp_f32_e32 v13, v13
	v_fma_f32 v20, -v18, v19, 1.0
	v_fmac_f32_e32 v19, v20, v19
	v_div_scale_f32 v20, vcc, 2.0, v10, 2.0
	v_mul_f32_e32 v21, v20, v19
	v_fma_f32 v22, -v18, v21, v20
	v_fmac_f32_e32 v21, v22, v19
	v_fma_f32 v18, -v18, v21, v20
	v_div_fmas_f32 v18, v18, v19, v21
	v_pk_add_f32 v[12:13], v[12:13], 1.0 op_sel_hi:[1,0]
	v_div_fixup_f32 v10, v18, v10, 2.0
	v_div_scale_f32 v18, s[4:5], v13, v13, 2.0
	v_rcp_f32_e32 v19, v18
	v_pk_add_f32 v[10:11], v[10:11], 1.0 op_sel_hi:[1,0] neg_lo:[1,0] neg_hi:[1,0]
	v_fma_f32 v20, -v18, v19, 1.0
	v_fmac_f32_e32 v19, v20, v19
	v_div_scale_f32 v20, vcc, 2.0, v13, 2.0
	v_mul_f32_e32 v21, v20, v19
	v_fma_f32 v22, -v18, v21, v20
	v_fmac_f32_e32 v21, v22, v19
	v_fma_f32 v18, -v18, v21, v20
	v_div_fmas_f32 v18, v18, v19, v21
	v_div_fixup_f32 v13, v18, v13, 2.0
	v_div_scale_f32 v18, s[4:5], v12, v12, 2.0
	v_rcp_f32_e32 v19, v18
	s_nop 0
	v_fma_f32 v20, -v18, v19, 1.0
	v_fmac_f32_e32 v19, v20, v19
	v_div_scale_f32 v20, vcc, 2.0, v12, 2.0
	v_mul_f32_e32 v21, v20, v19
	v_fma_f32 v22, -v18, v21, v20
	v_fmac_f32_e32 v21, v22, v19
	v_fma_f32 v18, -v18, v21, v20
	v_div_fmas_f32 v18, v18, v19, v21
	v_div_fixup_f32 v12, v18, v12, 2.0
	v_sub_f32_e32 v19, v16, v5
	v_sub_f32_e32 v18, v14, v4
	v_pk_fma_f32 v[0:1], v[0:1], v[18:19], v[4:5]
	v_sub_f32_e32 v16, v15, v6
	v_add_f32_e32 v0, v0, v0
	v_add_f32_e32 v1, v1, v1
	v_mul_f32_e32 v0, 0x3fb8aa3b, v0
	v_mul_f32_e32 v1, 0x3fb8aa3b, v1
	v_exp_f32_e32 v0, v0
	v_exp_f32_e32 v1, v1
	v_pk_fma_f32 v[2:3], v[2:3], v[16:17], v[6:7]
	v_pk_add_f32 v[12:13], v[12:13], 1.0 op_sel_hi:[1,0] neg_lo:[1,0] neg_hi:[1,0]
	v_pk_add_f32 v[0:1], v[0:1], 1.0 op_sel_hi:[1,0]
	s_nop 0
	v_div_scale_f32 v4, s[4:5], v1, v1, 2.0
	v_rcp_f32_e32 v5, v4
	s_nop 0
	v_fma_f32 v6, -v4, v5, 1.0
	v_fmac_f32_e32 v5, v6, v5
	v_div_scale_f32 v6, vcc, 2.0, v1, 2.0
	v_mul_f32_e32 v7, v6, v5
	v_fma_f32 v14, -v4, v7, v6
	v_fmac_f32_e32 v7, v14, v5
	v_fma_f32 v4, -v4, v7, v6
	v_div_fmas_f32 v4, v4, v5, v7
	v_div_fixup_f32 v1, v4, v1, 2.0
	v_div_scale_f32 v4, s[4:5], v0, v0, 2.0
	v_rcp_f32_e32 v5, v4
	s_nop 0
	v_fma_f32 v6, -v4, v5, 1.0
	v_fmac_f32_e32 v5, v6, v5
	v_div_scale_f32 v6, vcc, 2.0, v0, 2.0
	v_mul_f32_e32 v7, v6, v5
	v_fma_f32 v14, -v4, v7, v6
	v_fmac_f32_e32 v7, v14, v5
	v_fma_f32 v4, -v4, v7, v6
	v_div_fmas_f32 v4, v4, v5, v7
	v_div_fixup_f32 v0, v4, v0, 2.0
	v_pk_add_f32 v[4:5], v[0:1], 1.0 op_sel_hi:[1,0] neg_lo:[1,0] neg_hi:[1,0]
	v_add_f32_e32 v0, v2, v2
	v_add_f32_e32 v1, v3, v3
	v_mul_f32_e32 v0, 0x3fb8aa3b, v0
	v_mul_f32_e32 v1, 0x3fb8aa3b, v1
	v_exp_f32_e32 v0, v0
	v_exp_f32_e32 v1, v1
	s_nop 0
	v_pk_add_f32 v[0:1], v[0:1], 1.0 op_sel_hi:[1,0]
	s_nop 0
	v_div_scale_f32 v2, s[4:5], v1, v1, 2.0
	v_rcp_f32_e32 v3, v2
	s_nop 0
	v_fma_f32 v6, -v2, v3, 1.0
	v_fmac_f32_e32 v3, v6, v3
	v_div_scale_f32 v6, vcc, 2.0, v1, 2.0
	v_mul_f32_e32 v7, v6, v3
	v_fma_f32 v14, -v2, v7, v6
	v_fmac_f32_e32 v7, v14, v3
	v_fma_f32 v2, -v2, v7, v6
	v_div_fmas_f32 v2, v2, v3, v7
	v_div_fixup_f32 v1, v2, v1, 2.0
	v_div_scale_f32 v2, s[4:5], v0, v0, 2.0
	v_rcp_f32_e32 v3, v2
	s_nop 0
	v_fma_f32 v6, -v2, v3, 1.0
	v_fmac_f32_e32 v3, v6, v3
	v_div_scale_f32 v6, vcc, 2.0, v0, 2.0
	v_mul_f32_e32 v7, v6, v3
	v_fma_f32 v14, -v2, v7, v6
	v_fmac_f32_e32 v7, v14, v3
	v_fma_f32 v2, -v2, v7, v6
	v_div_fmas_f32 v2, v2, v3, v7
	v_div_fixup_f32 v0, v2, v0, 2.0
	v_pk_add_f32 v[6:7], v[0:1], 1.0 op_sel_hi:[1,0] neg_lo:[1,0] neg_hi:[1,0]
	v_cvt_pk_bf16_f32 v0, v10, v11
	v_cvt_pk_bf16_f32 v1, v12, v13
	v_cvt_pk_bf16_f32 v2, v4, v5
	v_cvt_pk_bf16_f32 v3, v6, v7
	global_load_dwordx4 v[4:7], v[36:37], off offset:2816
	v_lshl_add_u64 v[12:13], v[40:41], 0, s[12:13]
	s_waitcnt vmcnt(0)
	v_lshlrev_b32_e32 v10, 16, v4
	v_and_b32_e32 v11, 0xffff0000, v4
	v_lshlrev_b32_e32 v18, 16, v5
	v_and_b32_e32 v19, 0xffff0000, v5
	v_lshlrev_b32_e32 v20, 16, v6
	v_and_b32_e32 v21, 0xffff0000, v6
	v_lshlrev_b32_e32 v22, 16, v7
	v_and_b32_e32 v23, 0xffff0000, v7
	global_load_dwordx4 v[4:7], v[38:39], off offset:2816
	s_waitcnt vmcnt(0)
	v_cndmask_b32_e64 v7, v7, 0, s[38:39]
	v_cndmask_b32_e64 v6, v6, 0, s[38:39]
	v_cndmask_b32_e64 v5, v5, 0, s[38:39]
	v_cndmask_b32_e64 v4, v4, 0, s[38:39]
	v_lshlrev_b32_e32 v26, 16, v4
	v_and_b32_e32 v27, 0xffff0000, v4
	v_lshlrev_b32_e32 v30, 16, v5
	v_and_b32_e32 v31, 0xffff0000, v5
	v_lshlrev_b32_e32 v42, 16, v6
	v_and_b32_e32 v43, 0xffff0000, v6
	v_lshlrev_b32_e32 v44, 16, v7
	v_and_b32_e32 v45, 0xffff0000, v7
	global_load_dwordx4 v[4:7], v[174:175], off offset:16
	global_load_dwordx4 v[14:17], v[174:175], off
	v_sub_f32_e32 v27, v27, v11
	v_sub_f32_e32 v26, v26, v10
	v_sub_f32_e32 v31, v31, v19
	v_sub_f32_e32 v30, v30, v18
	s_waitcnt vmcnt(0)
	v_pk_fma_f32 v[16:17], v[16:17], v[30:31], v[18:19]
	v_pk_fma_f32 v[10:11], v[14:15], v[26:27], v[10:11]
	v_sub_f32_e32 v15, v43, v21
	v_sub_f32_e32 v14, v42, v20
	v_sub_f32_e32 v19, v45, v23
	v_sub_f32_e32 v18, v44, v22
	v_pk_fma_f32 v[18:19], v[6:7], v[18:19], v[22:23]
	v_pk_fma_f32 v[6:7], v[4:5], v[14:15], v[20:21]
	v_cvt_pk_bf16_f32 v4, v10, v11
	v_cvt_pk_bf16_f32 v5, v16, v17
	v_cvt_pk_bf16_f32 v6, v6, v7
	v_cvt_pk_bf16_f32 v7, v18, v19
	global_load_dwordx4 v[14:17], v[24:25], off offset:64
	s_nop 0
	global_load_dwordx4 v[8:11], v[8:9], off offset:64
	s_waitcnt vmcnt(1)
	v_lshlrev_b32_e32 v26, 16, v14
	v_and_b32_e32 v27, 0xffff0000, v14
	s_waitcnt vmcnt(0)
	v_cndmask_b32_e64 v11, v11, 0, s[38:39]
	v_cndmask_b32_e64 v10, v10, 0, s[38:39]
	v_cndmask_b32_e64 v9, v9, 0, s[38:39]
	v_cndmask_b32_e64 v8, v8, 0, s[38:39]
	v_lshlrev_b32_e32 v42, 16, v8
	v_and_b32_e32 v43, 0xffff0000, v8
	v_lshlrev_b32_e32 v44, 16, v9
	v_and_b32_e32 v45, 0xffff0000, v9
	v_lshlrev_b32_e32 v22, 16, v10
	v_and_b32_e32 v46, 0xffff0000, v10
	v_lshlrev_b32_e32 v23, 16, v11
	v_and_b32_e32 v47, 0xffff0000, v11
	global_load_dwordx4 v[8:11], v[172:173], off offset:144
	global_load_dwordx4 v[18:21], v[172:173], off offset:128
	v_sub_f32_e32 v43, v43, v27
	v_sub_f32_e32 v42, v42, v26
	v_lshlrev_b32_e32 v30, 16, v15
	v_and_b32_e32 v31, 0xffff0000, v15
	v_sub_f32_e32 v45, v45, v31
	v_sub_f32_e32 v44, v44, v30
	v_lshlrev_b32_e32 v14, 16, v16
	v_and_b32_e32 v15, 0xffff0000, v16
	v_lshlrev_b32_e32 v16, 16, v17
	v_and_b32_e32 v17, 0xffff0000, v17
	s_waitcnt vmcnt(0)
	v_pk_fma_f32 v[18:19], v[18:19], v[42:43], v[26:27]
	s_nop 0
	v_add_f32_e32 v18, v18, v18
	v_add_f32_e32 v19, v19, v19
	v_mul_f32_e32 v18, 0x3fb8aa3b, v18
	v_mul_f32_e32 v19, 0x3fb8aa3b, v19
	v_exp_f32_e32 v18, v18
	v_exp_f32_e32 v19, v19
	v_pk_fma_f32 v[20:21], v[20:21], v[44:45], v[30:31]
	v_pk_add_f32 v[18:19], v[18:19], 1.0 op_sel_hi:[1,0]
	s_nop 0
	v_div_scale_f32 v26, s[4:5], v19, v19, 2.0
	v_rcp_f32_e32 v27, v26
	v_add_f32_e32 v20, v20, v20
	v_add_f32_e32 v21, v21, v21
	v_mul_f32_e32 v20, 0x3fb8aa3b, v20
	v_fma_f32 v30, -v26, v27, 1.0
	v_fmac_f32_e32 v27, v30, v27
	v_div_scale_f32 v30, vcc, 2.0, v19, 2.0
	v_mul_f32_e32 v31, v30, v27
	v_fma_f32 v42, -v26, v31, v30
	v_fmac_f32_e32 v31, v42, v27
	v_fma_f32 v26, -v26, v31, v30
	v_div_fmas_f32 v26, v26, v27, v31
	v_div_fixup_f32 v19, v26, v19, 2.0
	v_div_scale_f32 v26, s[4:5], v18, v18, 2.0
	v_rcp_f32_e32 v27, v26
	v_mul_f32_e32 v21, 0x3fb8aa3b, v21
	v_exp_f32_e32 v20, v20
	v_exp_f32_e32 v21, v21
	v_fma_f32 v30, -v26, v27, 1.0
	v_fmac_f32_e32 v27, v30, v27
	v_div_scale_f32 v30, vcc, 2.0, v18, 2.0
	v_mul_f32_e32 v31, v30, v27
	v_fma_f32 v42, -v26, v31, v30
	v_fmac_f32_e32 v31, v42, v27
	v_fma_f32 v26, -v26, v31, v30
	v_div_fmas_f32 v26, v26, v27, v31
	v_pk_add_f32 v[20:21], v[20:21], 1.0 op_sel_hi:[1,0]
	v_div_fixup_f32 v18, v26, v18, 2.0
	v_div_scale_f32 v26, s[4:5], v21, v21, 2.0
	v_rcp_f32_e32 v27, v26
	v_pk_add_f32 v[18:19], v[18:19], 1.0 op_sel_hi:[1,0] neg_lo:[1,0] neg_hi:[1,0]
	v_fma_f32 v30, -v26, v27, 1.0
	v_fmac_f32_e32 v27, v30, v27
	v_div_scale_f32 v30, vcc, 2.0, v21, 2.0
	v_mul_f32_e32 v31, v30, v27
	v_fma_f32 v42, -v26, v31, v30
	v_fmac_f32_e32 v31, v42, v27
	v_fma_f32 v26, -v26, v31, v30
	v_div_fmas_f32 v26, v26, v27, v31
	v_div_fixup_f32 v21, v26, v21, 2.0
	v_div_scale_f32 v26, s[4:5], v20, v20, 2.0
	v_rcp_f32_e32 v27, v26
	s_nop 0
	v_fma_f32 v30, -v26, v27, 1.0
	v_fmac_f32_e32 v27, v30, v27
	v_div_scale_f32 v30, vcc, 2.0, v20, 2.0
	v_mul_f32_e32 v31, v30, v27
	v_fma_f32 v42, -v26, v31, v30
	v_fmac_f32_e32 v31, v42, v27
	v_fma_f32 v26, -v26, v31, v30
	v_div_fmas_f32 v26, v26, v27, v31
	v_div_fixup_f32 v20, v26, v20, 2.0
	v_sub_f32_e32 v27, v46, v15
	v_sub_f32_e32 v26, v22, v14
	v_pk_fma_f32 v[8:9], v[8:9], v[26:27], v[14:15]
	v_sub_f32_e32 v31, v47, v17
	v_add_f32_e32 v8, v8, v8
	v_add_f32_e32 v9, v9, v9
	v_mul_f32_e32 v8, 0x3fb8aa3b, v8
	v_mul_f32_e32 v9, 0x3fb8aa3b, v9
	v_exp_f32_e32 v8, v8
	v_exp_f32_e32 v9, v9
	v_sub_f32_e32 v30, v23, v16
	v_pk_fma_f32 v[10:11], v[10:11], v[30:31], v[16:17]
	v_pk_add_f32 v[20:21], v[20:21], 1.0 op_sel_hi:[1,0] neg_lo:[1,0] neg_hi:[1,0]
	v_pk_add_f32 v[8:9], v[8:9], 1.0 op_sel_hi:[1,0]
	s_nop 0
	v_div_scale_f32 v14, s[4:5], v9, v9, 2.0
	v_rcp_f32_e32 v15, v14
	s_nop 0
	v_fma_f32 v16, -v14, v15, 1.0
	v_fmac_f32_e32 v15, v16, v15
	v_div_scale_f32 v16, vcc, 2.0, v9, 2.0
	v_mul_f32_e32 v17, v16, v15
	v_fma_f32 v22, -v14, v17, v16
	v_fmac_f32_e32 v17, v22, v15
	v_fma_f32 v14, -v14, v17, v16
	v_div_fmas_f32 v14, v14, v15, v17
	v_div_fixup_f32 v9, v14, v9, 2.0
	v_div_scale_f32 v14, s[4:5], v8, v8, 2.0
	v_rcp_f32_e32 v15, v14
	s_nop 0
	v_fma_f32 v16, -v14, v15, 1.0
	v_fmac_f32_e32 v15, v16, v15
	v_div_scale_f32 v16, vcc, 2.0, v8, 2.0
	v_mul_f32_e32 v17, v16, v15
	v_fma_f32 v22, -v14, v17, v16
	v_fmac_f32_e32 v17, v22, v15
	v_fma_f32 v14, -v14, v17, v16
	v_div_fmas_f32 v14, v14, v15, v17
	v_div_fixup_f32 v8, v14, v8, 2.0
	v_pk_add_f32 v[14:15], v[8:9], 1.0 op_sel_hi:[1,0] neg_lo:[1,0] neg_hi:[1,0]
	v_add_f32_e32 v8, v10, v10
	v_add_f32_e32 v9, v11, v11
	v_mul_f32_e32 v8, 0x3fb8aa3b, v8
	v_mul_f32_e32 v9, 0x3fb8aa3b, v9
	v_exp_f32_e32 v8, v8
	v_exp_f32_e32 v9, v9
	s_nop 0
	v_pk_add_f32 v[8:9], v[8:9], 1.0 op_sel_hi:[1,0]
	s_nop 0
	v_div_scale_f32 v10, s[4:5], v9, v9, 2.0
	v_rcp_f32_e32 v11, v10
	s_nop 0
	v_fma_f32 v16, -v10, v11, 1.0
	v_fmac_f32_e32 v11, v16, v11
	v_div_scale_f32 v16, vcc, 2.0, v9, 2.0
	v_mul_f32_e32 v17, v16, v11
	v_fma_f32 v22, -v10, v17, v16
	v_fmac_f32_e32 v17, v22, v11
	v_fma_f32 v10, -v10, v17, v16
	v_div_fmas_f32 v10, v10, v11, v17
	v_div_fixup_f32 v9, v10, v9, 2.0
	v_div_scale_f32 v10, s[4:5], v8, v8, 2.0
	v_rcp_f32_e32 v11, v10
	s_nop 0
	v_fma_f32 v16, -v10, v11, 1.0
	v_fmac_f32_e32 v11, v16, v11
	v_div_scale_f32 v16, vcc, 2.0, v8, 2.0
	v_mul_f32_e32 v17, v16, v11
	v_fma_f32 v22, -v10, v17, v16
	v_fmac_f32_e32 v17, v22, v11
	v_fma_f32 v10, -v10, v17, v16
	v_div_fmas_f32 v10, v10, v11, v17
	v_div_fixup_f32 v8, v10, v8, 2.0
	v_pk_add_f32 v[16:17], v[8:9], 1.0 op_sel_hi:[1,0] neg_lo:[1,0] neg_hi:[1,0]
	v_cvt_pk_bf16_f32 v8, v18, v19
	v_cvt_pk_bf16_f32 v9, v20, v21
	v_cvt_pk_bf16_f32 v10, v14, v15
	v_cvt_pk_bf16_f32 v11, v16, v17
	global_load_dwordx4 v[14:17], v[28:29], off offset:64
	s_waitcnt vmcnt(0)
	v_lshlrev_b32_e32 v20, 16, v14
	v_and_b32_e32 v21, 0xffff0000, v14
	v_lshlrev_b32_e32 v22, 16, v15
	v_and_b32_e32 v23, 0xffff0000, v15
	global_load_dwordx4 v[12:15], v[12:13], off offset:64
	v_lshlrev_b32_e32 v26, 16, v16
	v_and_b32_e32 v27, 0xffff0000, v16
	v_lshlrev_b32_e32 v30, 16, v17
	v_and_b32_e32 v31, 0xffff0000, v17
	s_waitcnt vmcnt(0)
	v_cndmask_b32_e64 v15, v15, 0, s[38:39]
	v_cndmask_b32_e64 v14, v14, 0, s[38:39]
	v_cndmask_b32_e64 v13, v13, 0, s[38:39]
	v_cndmask_b32_e64 v12, v12, 0, s[38:39]
	v_lshlrev_b32_e32 v42, 16, v12
	v_and_b32_e32 v43, 0xffff0000, v12
	v_lshlrev_b32_e32 v44, 16, v13
	v_and_b32_e32 v45, 0xffff0000, v13
	v_lshlrev_b32_e32 v46, 16, v14
	v_and_b32_e32 v47, 0xffff0000, v14
	v_lshlrev_b32_e32 v48, 16, v15
	v_and_b32_e32 v49, 0xffff0000, v15
	global_load_dwordx4 v[12:15], v[174:175], off offset:144
	global_load_dwordx4 v[16:19], v[174:175], off offset:128
	v_sub_f32_e32 v43, v43, v21
	v_sub_f32_e32 v42, v42, v20
	v_sub_f32_e32 v45, v45, v23
	v_sub_f32_e32 v44, v44, v22
	s_waitcnt vmcnt(0)
	v_pk_fma_f32 v[18:19], v[18:19], v[44:45], v[22:23]
	v_pk_fma_f32 v[16:17], v[16:17], v[42:43], v[20:21]
	v_sub_f32_e32 v21, v47, v27
	v_sub_f32_e32 v20, v46, v26
	v_sub_f32_e32 v23, v49, v31
	v_sub_f32_e32 v22, v48, v30
	v_pk_fma_f32 v[22:23], v[14:15], v[22:23], v[30:31]
	v_pk_fma_f32 v[14:15], v[12:13], v[20:21], v[26:27]
	v_cvt_pk_bf16_f32 v12, v16, v17
	v_cvt_pk_bf16_f32 v13, v18, v19
	v_cvt_pk_bf16_f32 v14, v14, v15
	v_cvt_pk_bf16_f32 v15, v22, v23
	global_load_dwordx4 v[16:19], v[24:25], off offset:128
	v_lshl_add_u64 v[26:27], v[32:33], 0, s[8:9]
	v_lshl_add_u64 v[30:31], v[32:33], 0, s[12:13]
	v_lshl_add_u64 v[32:33], v[32:33], 0, v[166:167]
	s_waitcnt vmcnt(0)
	v_lshlrev_b32_e32 v46, 16, v16
	v_and_b32_e32 v47, 0xffff0000, v16
	v_lshlrev_b32_e32 v48, 16, v17
	v_and_b32_e32 v49, 0xffff0000, v17
	v_lshl_add_u64 v[16:17], v[26:27], 0, v[186:187]
	v_lshlrev_b32_e32 v20, 16, v18
	v_and_b32_e32 v21, 0xffff0000, v18
	v_lshlrev_b32_e32 v22, 16, v19
	v_and_b32_e32 v23, 0xffff0000, v19
	global_load_dwordx4 v[16:19], v[16:17], off
	s_waitcnt vmcnt(0)
	v_cndmask_b32_e64 v19, v19, 0, s[36:37]
	v_cndmask_b32_e64 v18, v18, 0, s[36:37]
	v_cndmask_b32_e64 v17, v17, 0, s[36:37]
	v_cndmask_b32_e64 v16, v16, 0, s[36:37]
	v_lshlrev_b32_e32 v50, 16, v16
	v_and_b32_e32 v51, 0xffff0000, v16
	v_lshlrev_b32_e32 v52, 16, v17
	v_and_b32_e32 v53, 0xffff0000, v17
	v_lshlrev_b32_e32 v54, 16, v18
	v_and_b32_e32 v55, 0xffff0000, v18
	v_lshlrev_b32_e32 v58, 16, v19
	v_and_b32_e32 v59, 0xffff0000, v19
	global_load_dwordx4 v[16:19], v[172:173], off offset:272
	global_load_dwordx4 v[42:45], v[172:173], off offset:256
	v_sub_f32_e32 v51, v51, v47
	v_sub_f32_e32 v50, v50, v46
	v_sub_f32_e32 v53, v53, v49
	v_sub_f32_e32 v52, v52, v48
	s_waitcnt vmcnt(0)
	v_pk_fma_f32 v[42:43], v[42:43], v[50:51], v[46:47]
	s_nop 0
	v_add_f32_e32 v42, v42, v42
	v_add_f32_e32 v43, v43, v43
	v_mul_f32_e32 v42, 0x3fb8aa3b, v42
	v_mul_f32_e32 v43, 0x3fb8aa3b, v43
	v_exp_f32_e32 v42, v42
	v_exp_f32_e32 v43, v43
	v_pk_fma_f32 v[44:45], v[44:45], v[52:53], v[48:49]
	v_pk_add_f32 v[42:43], v[42:43], 1.0 op_sel_hi:[1,0]
	s_nop 0
	v_div_scale_f32 v46, s[4:5], v43, v43, 2.0
	v_rcp_f32_e32 v47, v46
	v_add_f32_e32 v44, v44, v44
	v_add_f32_e32 v45, v45, v45
	v_mul_f32_e32 v44, 0x3fb8aa3b, v44
	v_fma_f32 v48, -v46, v47, 1.0
	v_fmac_f32_e32 v47, v48, v47
	v_div_scale_f32 v48, vcc, 2.0, v43, 2.0
	v_mul_f32_e32 v49, v48, v47
	v_fma_f32 v50, -v46, v49, v48
	v_fmac_f32_e32 v49, v50, v47
	v_fma_f32 v46, -v46, v49, v48
	v_div_fmas_f32 v46, v46, v47, v49
	v_div_fixup_f32 v43, v46, v43, 2.0
	v_div_scale_f32 v46, s[4:5], v42, v42, 2.0
	v_rcp_f32_e32 v47, v46
	v_mul_f32_e32 v45, 0x3fb8aa3b, v45
	v_exp_f32_e32 v44, v44
	v_exp_f32_e32 v45, v45
	v_fma_f32 v48, -v46, v47, 1.0
	v_fmac_f32_e32 v47, v48, v47
	v_div_scale_f32 v48, vcc, 2.0, v42, 2.0
	v_mul_f32_e32 v49, v48, v47
	v_fma_f32 v50, -v46, v49, v48
	v_fmac_f32_e32 v49, v50, v47
	v_fma_f32 v46, -v46, v49, v48
	v_div_fmas_f32 v46, v46, v47, v49
	v_pk_add_f32 v[44:45], v[44:45], 1.0 op_sel_hi:[1,0]
	v_div_fixup_f32 v42, v46, v42, 2.0
	v_div_scale_f32 v46, s[4:5], v45, v45, 2.0
	v_rcp_f32_e32 v47, v46
	v_pk_add_f32 v[42:43], v[42:43], 1.0 op_sel_hi:[1,0] neg_lo:[1,0] neg_hi:[1,0]
	v_fma_f32 v48, -v46, v47, 1.0
	v_fmac_f32_e32 v47, v48, v47
	v_div_scale_f32 v48, vcc, 2.0, v45, 2.0
	v_mul_f32_e32 v49, v48, v47
	v_fma_f32 v50, -v46, v49, v48
	v_fmac_f32_e32 v49, v50, v47
	v_fma_f32 v46, -v46, v49, v48
	v_div_fmas_f32 v46, v46, v47, v49
	v_div_fixup_f32 v45, v46, v45, 2.0
	v_div_scale_f32 v46, s[4:5], v44, v44, 2.0
	v_rcp_f32_e32 v47, v46
	s_nop 0
	v_fma_f32 v48, -v46, v47, 1.0
	v_fmac_f32_e32 v47, v48, v47
	v_div_scale_f32 v48, vcc, 2.0, v44, 2.0
	v_mul_f32_e32 v49, v48, v47
	v_fma_f32 v50, -v46, v49, v48
	v_fmac_f32_e32 v49, v50, v47
	v_fma_f32 v46, -v46, v49, v48
	v_div_fmas_f32 v46, v46, v47, v49
	v_div_fixup_f32 v44, v46, v44, 2.0
	v_sub_f32_e32 v47, v55, v21
	v_sub_f32_e32 v46, v54, v20
	v_pk_fma_f32 v[16:17], v[16:17], v[46:47], v[20:21]
	v_sub_f32_e32 v49, v59, v23
	v_add_f32_e32 v16, v16, v16
	v_add_f32_e32 v17, v17, v17
	v_mul_f32_e32 v16, 0x3fb8aa3b, v16
	v_mul_f32_e32 v17, 0x3fb8aa3b, v17
	v_exp_f32_e32 v16, v16
	v_exp_f32_e32 v17, v17
	v_sub_f32_e32 v48, v58, v22
	v_pk_fma_f32 v[18:19], v[18:19], v[48:49], v[22:23]
	v_pk_add_f32 v[44:45], v[44:45], 1.0 op_sel_hi:[1,0] neg_lo:[1,0] neg_hi:[1,0]
	v_pk_add_f32 v[16:17], v[16:17], 1.0 op_sel_hi:[1,0]
	s_nop 0
	v_div_scale_f32 v20, s[4:5], v17, v17, 2.0
	v_rcp_f32_e32 v21, v20
	s_nop 0
	v_fma_f32 v22, -v20, v21, 1.0
	v_fmac_f32_e32 v21, v22, v21
	v_div_scale_f32 v22, vcc, 2.0, v17, 2.0
	v_mul_f32_e32 v23, v22, v21
	v_fma_f32 v46, -v20, v23, v22
	v_fmac_f32_e32 v23, v46, v21
	v_fma_f32 v20, -v20, v23, v22
	v_div_fmas_f32 v20, v20, v21, v23
	v_div_fixup_f32 v17, v20, v17, 2.0
	v_div_scale_f32 v20, s[4:5], v16, v16, 2.0
	v_rcp_f32_e32 v21, v20
	s_nop 0
	v_fma_f32 v22, -v20, v21, 1.0
	v_fmac_f32_e32 v21, v22, v21
	v_div_scale_f32 v22, vcc, 2.0, v16, 2.0
	v_mul_f32_e32 v23, v22, v21
	v_fma_f32 v46, -v20, v23, v22
	v_fmac_f32_e32 v23, v46, v21
	v_fma_f32 v20, -v20, v23, v22
	v_div_fmas_f32 v20, v20, v21, v23
	v_div_fixup_f32 v16, v20, v16, 2.0
	v_pk_add_f32 v[20:21], v[16:17], 1.0 op_sel_hi:[1,0] neg_lo:[1,0] neg_hi:[1,0]
	v_add_f32_e32 v16, v18, v18
	v_add_f32_e32 v17, v19, v19
	v_mul_f32_e32 v16, 0x3fb8aa3b, v16
	v_mul_f32_e32 v17, 0x3fb8aa3b, v17
	v_exp_f32_e32 v16, v16
	v_exp_f32_e32 v17, v17
	s_nop 0
	v_pk_add_f32 v[16:17], v[16:17], 1.0 op_sel_hi:[1,0]
	s_nop 0
	v_div_scale_f32 v18, s[4:5], v17, v17, 2.0
	v_rcp_f32_e32 v19, v18
	s_nop 0
	v_fma_f32 v22, -v18, v19, 1.0
	v_fmac_f32_e32 v19, v22, v19
	v_div_scale_f32 v22, vcc, 2.0, v17, 2.0
	v_mul_f32_e32 v23, v22, v19
	v_fma_f32 v46, -v18, v23, v22
	v_fmac_f32_e32 v23, v46, v19
	v_fma_f32 v18, -v18, v23, v22
	v_div_fmas_f32 v18, v18, v19, v23
	v_div_fixup_f32 v17, v18, v17, 2.0
	v_div_scale_f32 v18, s[4:5], v16, v16, 2.0
	v_rcp_f32_e32 v19, v18
	s_nop 0
	v_fma_f32 v22, -v18, v19, 1.0
	v_fmac_f32_e32 v19, v22, v19
	v_div_scale_f32 v22, vcc, 2.0, v16, 2.0
	v_mul_f32_e32 v23, v22, v19
	v_fma_f32 v46, -v18, v23, v22
	v_fmac_f32_e32 v23, v46, v19
	v_fma_f32 v18, -v18, v23, v22
	v_div_fmas_f32 v18, v18, v19, v23
	v_div_fixup_f32 v16, v18, v16, 2.0
	v_pk_add_f32 v[22:23], v[16:17], 1.0 op_sel_hi:[1,0] neg_lo:[1,0] neg_hi:[1,0]
	v_cvt_pk_bf16_f32 v16, v42, v43
	v_cvt_pk_bf16_f32 v17, v44, v45
	v_cvt_pk_bf16_f32 v18, v20, v21
	v_cvt_pk_bf16_f32 v19, v22, v23
	global_load_dwordx4 v[20:23], v[28:29], off offset:128
	s_waitcnt vmcnt(0)
	v_lshlrev_b32_e32 v46, 16, v20
	v_and_b32_e32 v47, 0xffff0000, v20
	v_lshlrev_b32_e32 v48, 16, v21
	v_and_b32_e32 v49, 0xffff0000, v21
	v_lshl_add_u64 v[20:21], v[30:31], 0, v[186:187]
	v_lshlrev_b32_e32 v50, 16, v22
	v_and_b32_e32 v51, 0xffff0000, v22
	v_lshlrev_b32_e32 v52, 16, v23
	v_and_b32_e32 v53, 0xffff0000, v23
	global_load_dwordx4 v[20:23], v[20:21], off
	s_waitcnt vmcnt(0)
	v_cndmask_b32_e64 v23, v23, 0, s[36:37]
	v_cndmask_b32_e64 v22, v22, 0, s[36:37]
	v_cndmask_b32_e64 v21, v21, 0, s[36:37]
	v_cndmask_b32_e64 v20, v20, 0, s[36:37]
	v_lshlrev_b32_e32 v54, 16, v20
	v_and_b32_e32 v55, 0xffff0000, v20
	v_lshlrev_b32_e32 v58, 16, v21
	v_and_b32_e32 v59, 0xffff0000, v21
	v_lshlrev_b32_e32 v60, 16, v22
	v_and_b32_e32 v61, 0xffff0000, v22
	v_lshlrev_b32_e32 v62, 16, v23
	v_and_b32_e32 v63, 0xffff0000, v23
	global_load_dwordx4 v[20:23], v[174:175], off offset:272
	global_load_dwordx4 v[42:45], v[174:175], off offset:256
	v_sub_f32_e32 v55, v55, v47
	v_sub_f32_e32 v54, v54, v46
	v_sub_f32_e32 v59, v59, v49
	v_sub_f32_e32 v58, v58, v48
	s_waitcnt vmcnt(0)
	v_pk_fma_f32 v[44:45], v[44:45], v[58:59], v[48:49]
	v_pk_fma_f32 v[42:43], v[42:43], v[54:55], v[46:47]
	v_sub_f32_e32 v47, v61, v51
	v_sub_f32_e32 v46, v60, v50
	v_sub_f32_e32 v49, v63, v53
	v_sub_f32_e32 v48, v62, v52
	v_pk_fma_f32 v[48:49], v[22:23], v[48:49], v[52:53]
	v_pk_fma_f32 v[22:23], v[20:21], v[46:47], v[50:51]
	v_cvt_pk_bf16_f32 v20, v42, v43
	v_cvt_pk_bf16_f32 v21, v44, v45
	v_cvt_pk_bf16_f32 v22, v22, v23
	v_cvt_pk_bf16_f32 v23, v48, v49
	global_load_dwordx4 v[42:45], v[24:25], off offset:192
	v_lshl_add_u64 v[24:25], v[26:27], 0, v[188:189]
	global_load_dwordx4 v[24:27], v[24:25], off
	s_waitcnt vmcnt(1)
	v_lshlrev_b32_e32 v50, 16, v42
	v_and_b32_e32 v51, 0xffff0000, v42
	s_waitcnt vmcnt(0)
	v_cndmask_b32_e64 v27, v27, 0, s[36:37]
	v_cndmask_b32_e64 v26, v26, 0, s[36:37]
	v_cndmask_b32_e64 v25, v25, 0, s[36:37]
	v_cndmask_b32_e64 v24, v24, 0, s[36:37]
	v_lshlrev_b32_e32 v54, 16, v24
	v_and_b32_e32 v55, 0xffff0000, v24
	v_lshlrev_b32_e32 v58, 16, v25
	v_and_b32_e32 v59, 0xffff0000, v25
	v_lshlrev_b32_e32 v60, 16, v26
	v_and_b32_e32 v61, 0xffff0000, v26
	v_lshlrev_b32_e32 v62, 16, v27
	v_and_b32_e32 v63, 0xffff0000, v27
	global_load_dwordx4 v[24:27], v[172:173], off offset:400
	global_load_dwordx4 v[46:49], v[172:173], off offset:384
	v_sub_f32_e32 v55, v55, v51
	v_sub_f32_e32 v54, v54, v50
	v_lshlrev_b32_e32 v52, 16, v43
	v_and_b32_e32 v53, 0xffff0000, v43
	v_sub_f32_e32 v59, v59, v53
	v_sub_f32_e32 v58, v58, v52
	v_lshlrev_b32_e32 v42, 16, v44
	v_and_b32_e32 v43, 0xffff0000, v44
	v_lshlrev_b32_e32 v44, 16, v45
	v_and_b32_e32 v45, 0xffff0000, v45
	s_waitcnt vmcnt(0)
	v_pk_fma_f32 v[46:47], v[46:47], v[54:55], v[50:51]
	s_nop 0
	v_add_f32_e32 v46, v46, v46
	v_add_f32_e32 v47, v47, v47
	v_mul_f32_e32 v46, 0x3fb8aa3b, v46
	v_mul_f32_e32 v47, 0x3fb8aa3b, v47
	v_exp_f32_e32 v46, v46
	v_exp_f32_e32 v47, v47
	v_pk_fma_f32 v[48:49], v[48:49], v[58:59], v[52:53]
	v_pk_add_f32 v[46:47], v[46:47], 1.0 op_sel_hi:[1,0]
	s_nop 0
	v_div_scale_f32 v50, s[4:5], v47, v47, 2.0
	v_rcp_f32_e32 v51, v50
	v_add_f32_e32 v48, v48, v48
	v_add_f32_e32 v49, v49, v49
	v_mul_f32_e32 v48, 0x3fb8aa3b, v48
	v_fma_f32 v52, -v50, v51, 1.0
	v_fmac_f32_e32 v51, v52, v51
	v_div_scale_f32 v52, vcc, 2.0, v47, 2.0
	v_mul_f32_e32 v53, v52, v51
	v_fma_f32 v54, -v50, v53, v52
	v_fmac_f32_e32 v53, v54, v51
	v_fma_f32 v50, -v50, v53, v52
	v_div_fmas_f32 v50, v50, v51, v53
	v_div_fixup_f32 v47, v50, v47, 2.0
	v_div_scale_f32 v50, s[4:5], v46, v46, 2.0
	v_rcp_f32_e32 v51, v50
	v_mul_f32_e32 v49, 0x3fb8aa3b, v49
	v_exp_f32_e32 v48, v48
	v_exp_f32_e32 v49, v49
	v_fma_f32 v52, -v50, v51, 1.0
	v_fmac_f32_e32 v51, v52, v51
	v_div_scale_f32 v52, vcc, 2.0, v46, 2.0
	v_mul_f32_e32 v53, v52, v51
	v_fma_f32 v54, -v50, v53, v52
	v_fmac_f32_e32 v53, v54, v51
	v_fma_f32 v50, -v50, v53, v52
	v_div_fmas_f32 v50, v50, v51, v53
	v_pk_add_f32 v[48:49], v[48:49], 1.0 op_sel_hi:[1,0]
	v_div_fixup_f32 v46, v50, v46, 2.0
	v_div_scale_f32 v50, s[4:5], v49, v49, 2.0
	v_rcp_f32_e32 v51, v50
	v_pk_add_f32 v[46:47], v[46:47], 1.0 op_sel_hi:[1,0] neg_lo:[1,0] neg_hi:[1,0]
	v_fma_f32 v52, -v50, v51, 1.0
	v_fmac_f32_e32 v51, v52, v51
	v_div_scale_f32 v52, vcc, 2.0, v49, 2.0
	v_mul_f32_e32 v53, v52, v51
	v_fma_f32 v54, -v50, v53, v52
	v_fmac_f32_e32 v53, v54, v51
	v_fma_f32 v50, -v50, v53, v52
	v_div_fmas_f32 v50, v50, v51, v53
	v_div_fixup_f32 v49, v50, v49, 2.0
	v_div_scale_f32 v50, s[4:5], v48, v48, 2.0
	v_rcp_f32_e32 v51, v50
	s_nop 0
	v_fma_f32 v52, -v50, v51, 1.0
	v_fmac_f32_e32 v51, v52, v51
	v_div_scale_f32 v52, vcc, 2.0, v48, 2.0
	v_mul_f32_e32 v53, v52, v51
	v_fma_f32 v54, -v50, v53, v52
	v_fmac_f32_e32 v53, v54, v51
	v_fma_f32 v50, -v50, v53, v52
	v_div_fmas_f32 v50, v50, v51, v53
	v_div_fixup_f32 v48, v50, v48, 2.0
	v_sub_f32_e32 v51, v61, v43
	v_sub_f32_e32 v50, v60, v42
	v_pk_fma_f32 v[24:25], v[24:25], v[50:51], v[42:43]
	v_sub_f32_e32 v53, v63, v45
	v_add_f32_e32 v24, v24, v24
	v_add_f32_e32 v25, v25, v25
	v_mul_f32_e32 v24, 0x3fb8aa3b, v24
	v_mul_f32_e32 v25, 0x3fb8aa3b, v25
	v_exp_f32_e32 v24, v24
	v_exp_f32_e32 v25, v25
	v_sub_f32_e32 v52, v62, v44
	v_pk_fma_f32 v[26:27], v[26:27], v[52:53], v[44:45]
	v_pk_add_f32 v[48:49], v[48:49], 1.0 op_sel_hi:[1,0] neg_lo:[1,0] neg_hi:[1,0]
	v_pk_add_f32 v[24:25], v[24:25], 1.0 op_sel_hi:[1,0]
	s_nop 0
	v_div_scale_f32 v42, s[4:5], v25, v25, 2.0
	v_rcp_f32_e32 v43, v42
	s_nop 0
	v_fma_f32 v44, -v42, v43, 1.0
	v_fmac_f32_e32 v43, v44, v43
	v_div_scale_f32 v44, vcc, 2.0, v25, 2.0
	v_mul_f32_e32 v45, v44, v43
	v_fma_f32 v50, -v42, v45, v44
	v_fmac_f32_e32 v45, v50, v43
	v_fma_f32 v42, -v42, v45, v44
	v_div_fmas_f32 v42, v42, v43, v45
	v_div_fixup_f32 v25, v42, v25, 2.0
	v_div_scale_f32 v42, s[4:5], v24, v24, 2.0
	v_rcp_f32_e32 v43, v42
	s_nop 0
	v_fma_f32 v44, -v42, v43, 1.0
	v_fmac_f32_e32 v43, v44, v43
	v_div_scale_f32 v44, vcc, 2.0, v24, 2.0
	v_mul_f32_e32 v45, v44, v43
	v_fma_f32 v50, -v42, v45, v44
	v_fmac_f32_e32 v45, v50, v43
	v_fma_f32 v42, -v42, v45, v44
	v_div_fmas_f32 v42, v42, v43, v45
	v_div_fixup_f32 v24, v42, v24, 2.0
	v_pk_add_f32 v[42:43], v[24:25], 1.0 op_sel_hi:[1,0] neg_lo:[1,0] neg_hi:[1,0]
	v_add_f32_e32 v24, v26, v26
	v_add_f32_e32 v25, v27, v27
	v_mul_f32_e32 v24, 0x3fb8aa3b, v24
	v_mul_f32_e32 v25, 0x3fb8aa3b, v25
	v_exp_f32_e32 v24, v24
	v_exp_f32_e32 v25, v25
	s_nop 0
	v_pk_add_f32 v[24:25], v[24:25], 1.0 op_sel_hi:[1,0]
	s_nop 0
	v_div_scale_f32 v26, s[4:5], v25, v25, 2.0
	v_rcp_f32_e32 v27, v26
	s_nop 0
	v_fma_f32 v44, -v26, v27, 1.0
	v_fmac_f32_e32 v27, v44, v27
	v_div_scale_f32 v44, vcc, 2.0, v25, 2.0
	v_mul_f32_e32 v45, v44, v27
	v_fma_f32 v50, -v26, v45, v44
	v_fmac_f32_e32 v45, v50, v27
	v_fma_f32 v26, -v26, v45, v44
	v_div_fmas_f32 v26, v26, v27, v45
	v_div_fixup_f32 v25, v26, v25, 2.0
	v_div_scale_f32 v26, s[4:5], v24, v24, 2.0
	v_rcp_f32_e32 v27, v26
	s_mov_b64 s[4:5], 0x2c00
	v_fma_f32 v44, -v26, v27, 1.0
	v_fmac_f32_e32 v27, v44, v27
	v_div_scale_f32 v44, vcc, 2.0, v24, 2.0
	v_mul_f32_e32 v45, v44, v27
	v_fma_f32 v50, -v26, v45, v44
	v_fmac_f32_e32 v45, v50, v27
	v_fma_f32 v26, -v26, v45, v44
	v_div_fmas_f32 v26, v26, v27, v45
	v_div_fixup_f32 v24, v26, v24, 2.0
	v_pk_add_f32 v[44:45], v[24:25], 1.0 op_sel_hi:[1,0] neg_lo:[1,0] neg_hi:[1,0]
	v_cvt_pk_bf16_f32 v24, v46, v47
	v_cvt_pk_bf16_f32 v25, v48, v49
	v_cvt_pk_bf16_f32 v26, v42, v43
	v_cvt_pk_bf16_f32 v27, v44, v45
	global_load_dwordx4 v[42:45], v[28:29], off offset:192
	v_lshl_add_u64 v[28:29], v[30:31], 0, v[188:189]
	global_load_dwordx4 v[28:31], v[28:29], off
	s_waitcnt vmcnt(1)
	v_lshlrev_b32_e32 v46, 16, v42
	v_and_b32_e32 v47, 0xffff0000, v42
	s_waitcnt vmcnt(0)
	v_cndmask_b32_e64 v31, v31, 0, s[36:37]
	v_cndmask_b32_e64 v30, v30, 0, s[36:37]
	v_cndmask_b32_e64 v29, v29, 0, s[36:37]
	v_cndmask_b32_e64 v28, v28, 0, s[36:37]
	v_lshlrev_b32_e32 v48, 16, v43
	v_and_b32_e32 v49, 0xffff0000, v43
	v_lshlrev_b32_e32 v50, 16, v44
	v_and_b32_e32 v51, 0xffff0000, v44
	v_lshlrev_b32_e32 v52, 16, v45
	v_and_b32_e32 v53, 0xffff0000, v45
	v_lshlrev_b32_e32 v54, 16, v28
	v_and_b32_e32 v55, 0xffff0000, v28
	v_lshlrev_b32_e32 v58, 16, v29
	v_and_b32_e32 v59, 0xffff0000, v29
	v_lshlrev_b32_e32 v60, 16, v30
	v_and_b32_e32 v61, 0xffff0000, v30
	v_lshlrev_b32_e32 v62, 16, v31
	v_and_b32_e32 v63, 0xffff0000, v31
	global_load_dwordx4 v[28:31], v[174:175], off offset:400
	global_load_dwordx4 v[42:45], v[174:175], off offset:384
	v_sub_f32_e32 v55, v55, v47
	v_sub_f32_e32 v54, v54, v46
	v_sub_f32_e32 v59, v59, v49
	v_sub_f32_e32 v58, v58, v48
	s_waitcnt vmcnt(0)
	v_pk_fma_f32 v[44:45], v[44:45], v[58:59], v[48:49]
	v_pk_fma_f32 v[42:43], v[42:43], v[54:55], v[46:47]
	v_sub_f32_e32 v47, v61, v51
	v_sub_f32_e32 v46, v60, v50
	v_sub_f32_e32 v49, v63, v53
	v_sub_f32_e32 v48, v62, v52
	v_pk_fma_f32 v[48:49], v[30:31], v[48:49], v[52:53]
	v_pk_fma_f32 v[30:31], v[28:29], v[46:47], v[50:51]
	v_cvt_pk_bf16_f32 v28, v42, v43
	v_cvt_pk_bf16_f32 v29, v44, v45
	v_cvt_pk_bf16_f32 v30, v30, v31
	v_cvt_pk_bf16_f32 v31, v48, v49
	v_lshl_add_u64 v[54:55], v[34:35], 0, s[4:5]
	global_load_dwordx4 v[34:37], v[36:37], off offset:3072
	v_lshl_add_u64 v[58:59], v[32:33], 0, s[4:5]
	v_add_co_u32_e32 v32, vcc, s79, v32
	v_lshl_add_u64 v[52:53], v[40:41], 0, s[4:5]
	s_nop 0
	v_addc_co_u32_e32 v33, vcc, 0, v33, vcc
	s_waitcnt vmcnt(0)
	v_lshlrev_b32_e32 v48, 16, v34
	v_and_b32_e32 v49, 0xffff0000, v34
	v_lshlrev_b32_e32 v46, 16, v35
	v_and_b32_e32 v47, 0xffff0000, v35
	v_lshlrev_b32_e32 v44, 16, v36
	v_and_b32_e32 v45, 0xffff0000, v36
	v_lshlrev_b32_e32 v42, 16, v37
	v_and_b32_e32 v43, 0xffff0000, v37
	global_load_dwordx4 v[34:37], v[38:39], off offset:3072
	s_waitcnt vmcnt(0)
	v_cndmask_b32_e64 v35, v35, 0, s[38:39]
	v_cndmask_b32_e64 v34, v34, 0, s[38:39]
	v_lshlrev_b32_e32 v70, 16, v34
	v_and_b32_e32 v71, 0xffff0000, v34
	v_lshlrev_b32_e32 v68, 16, v35
	v_and_b32_e32 v69, 0xffff0000, v35
	global_load_dwordx4 v[32:35], v[32:33], off offset:3072
	v_cndmask_b32_e64 v37, v37, 0, s[38:39]
	v_cndmask_b32_e64 v36, v36, 0, s[38:39]
	v_lshlrev_b32_e32 v40, 16, v36
	v_and_b32_e32 v41, 0xffff0000, v36
	v_lshlrev_b32_e32 v50, 16, v37
	v_and_b32_e32 v51, 0xffff0000, v37
	v_sub_f32_e32 v71, v71, v49
	v_sub_f32_e32 v70, v70, v48
	v_sub_f32_e32 v69, v69, v47
	v_sub_f32_e32 v68, v68, v46
	v_sub_f32_e32 v41, v41, v45
	v_sub_f32_e32 v40, v40, v44
	s_waitcnt vmcnt(0)
	v_cndmask_b32_e64 v35, v35, 0, s[36:37]
	v_cndmask_b32_e64 v34, v34, 0, s[36:37]
	v_cndmask_b32_e64 v33, v33, 0, s[36:37]
	v_cndmask_b32_e64 v32, v32, 0, s[36:37]
	v_lshlrev_b32_e32 v72, 16, v32
	v_and_b32_e32 v73, 0xffff0000, v32
	v_lshlrev_b32_e32 v74, 16, v33
	v_and_b32_e32 v75, 0xffff0000, v33
	v_lshlrev_b32_e32 v76, 16, v34
	v_and_b32_e32 v77, 0xffff0000, v34
	v_lshlrev_b32_e32 v78, 16, v35
	v_and_b32_e32 v79, 0xffff0000, v35
	global_load_dwordx4 v[32:35], v[176:177], off offset:16
	global_load_dwordx4 v[60:63], v[176:177], off
	global_load_dwordx4 v[36:39], v[176:177], off offset:656
	global_load_dwordx4 v[64:67], v[176:177], off offset:640
	s_waitcnt vmcnt(3)
	v_pk_fma_f32 v[32:33], v[32:33], v[40:41], v[44:45]
	s_waitcnt vmcnt(2)
	v_pk_fma_f32 v[60:61], v[60:61], v[70:71], v[48:49]
	v_sub_f32_e32 v49, v73, v49
	v_sub_f32_e32 v48, v72, v48
	s_waitcnt vmcnt(0)
	v_pk_fma_f32 v[48:49], v[64:65], v[48:49], v[60:61]
	v_pk_fma_f32 v[62:63], v[62:63], v[68:69], v[46:47]
	v_mul_f32_e32 v48, 0xbfb8aa3b, v48
	v_mul_f32_e32 v49, 0xbfb8aa3b, v49
	v_exp_f32_e32 v48, v48
	v_exp_f32_e32 v49, v49
	v_sub_f32_e32 v47, v75, v47
	v_sub_f32_e32 v46, v74, v46
	v_pk_fma_f32 v[46:47], v[66:67], v[46:47], v[62:63]
	v_pk_add_f32 v[48:49], v[48:49], 1.0 op_sel_hi:[1,0]
	v_mul_f32_e32 v46, 0xbfb8aa3b, v46
	v_div_scale_f32 v60, s[4:5], v49, v49, 1.0
	v_rcp_f32_e32 v61, v60
	v_mul_f32_e32 v47, 0xbfb8aa3b, v47
	v_exp_f32_e32 v46, v46
	v_exp_f32_e32 v47, v47
	v_fma_f32 v62, -v60, v61, 1.0
	v_fmac_f32_e32 v61, v62, v61
	v_div_scale_f32 v62, vcc, 1.0, v49, 1.0
	v_mul_f32_e32 v63, v62, v61
	v_fma_f32 v64, -v60, v63, v62
	v_fmac_f32_e32 v63, v64, v61
	v_fma_f32 v60, -v60, v63, v62
	v_div_fmas_f32 v60, v60, v61, v63
	v_div_fixup_f32 v49, v60, v49, 1.0
	v_div_scale_f32 v60, s[4:5], v48, v48, 1.0
	v_rcp_f32_e32 v61, v60
	v_pk_add_f32 v[46:47], v[46:47], 1.0 op_sel_hi:[1,0]
	v_sub_f32_e32 v41, v77, v45
	v_sub_f32_e32 v40, v76, v44
	v_fma_f32 v62, -v60, v61, 1.0
	v_fmac_f32_e32 v61, v62, v61
	v_div_scale_f32 v62, vcc, 1.0, v48, 1.0
	v_mul_f32_e32 v63, v62, v61
	v_fma_f32 v64, -v60, v63, v62
	v_fmac_f32_e32 v63, v64, v61
	v_fma_f32 v60, -v60, v63, v62
	v_div_fmas_f32 v60, v60, v61, v63
	v_div_fixup_f32 v48, v60, v48, 1.0
	v_div_scale_f32 v60, s[4:5], v47, v47, 1.0
	v_rcp_f32_e32 v61, v60
	v_pk_fma_f32 v[32:33], v[36:37], v[40:41], v[32:33]
	v_fma_f32 v62, -v60, v61, 1.0
	v_fmac_f32_e32 v61, v62, v61
	v_div_scale_f32 v62, vcc, 1.0, v47, 1.0
	v_mul_f32_e32 v63, v62, v61
	v_fma_f32 v64, -v60, v63, v62
	v_fmac_f32_e32 v63, v64, v61
	v_fma_f32 v60, -v60, v63, v62
	v_div_fmas_f32 v60, v60, v61, v63
	v_div_fixup_f32 v60, v60, v47, 1.0
	v_div_scale_f32 v47, s[4:5], v46, v46, 1.0
	v_rcp_f32_e32 v61, v47
	v_mul_f32_e32 v32, 0xbfb8aa3b, v32
	v_mul_f32_e32 v33, 0xbfb8aa3b, v33
	v_exp_f32_e32 v32, v32
	v_exp_f32_e32 v33, v33
	v_fma_f32 v62, -v47, v61, 1.0
	v_fmac_f32_e32 v61, v62, v61
	v_div_scale_f32 v62, vcc, 1.0, v46, 1.0
	v_mul_f32_e32 v63, v62, v61
	v_fma_f32 v64, -v47, v63, v62
	v_pk_add_f32 v[32:33], v[32:33], 1.0 op_sel_hi:[1,0]
	v_fmac_f32_e32 v63, v64, v61
	v_div_scale_f32 v36, s[4:5], v33, v33, 1.0
	v_fma_f32 v47, -v47, v63, v62
	v_rcp_f32_e32 v37, v36
	v_div_fmas_f32 v47, v47, v61, v63
	v_div_fixup_f32 v61, v47, v46, 1.0
	v_sub_f32_e32 v47, v51, v43
	v_sub_f32_e32 v46, v50, v42
	v_pk_fma_f32 v[34:35], v[34:35], v[46:47], v[42:43]
	v_sub_f32_e32 v43, v79, v43
	v_sub_f32_e32 v42, v78, v42
	v_pk_fma_f32 v[34:35], v[38:39], v[42:43], v[34:35]
	v_fma_f32 v38, -v36, v37, 1.0
	v_fmac_f32_e32 v37, v38, v37
	v_div_scale_f32 v38, vcc, 1.0, v33, 1.0
	v_mul_f32_e32 v39, v38, v37
	v_fma_f32 v40, -v36, v39, v38
	v_fmac_f32_e32 v39, v40, v37
	v_fma_f32 v36, -v36, v39, v38
	v_div_fmas_f32 v36, v36, v37, v39
	v_div_fixup_f32 v36, v36, v33, 1.0
	v_div_scale_f32 v33, s[4:5], v32, v32, 1.0
	v_rcp_f32_e32 v37, v33
	s_nop 0
	v_fma_f32 v38, -v33, v37, 1.0
	v_fmac_f32_e32 v37, v38, v37
	v_div_scale_f32 v38, vcc, 1.0, v32, 1.0
	v_mul_f32_e32 v39, v38, v37
	v_fma_f32 v40, -v33, v39, v38
	v_fmac_f32_e32 v39, v40, v37
	v_fma_f32 v33, -v33, v39, v38
	v_div_fmas_f32 v33, v33, v37, v39
	v_div_fixup_f32 v37, v33, v32, 1.0
	v_mul_f32_e32 v32, 0xbfb8aa3b, v34
	v_mul_f32_e32 v33, 0xbfb8aa3b, v35
	v_exp_f32_e32 v32, v32
	v_exp_f32_e32 v33, v33
	s_nop 0
	v_pk_add_f32 v[32:33], v[32:33], 1.0 op_sel_hi:[1,0]
	s_nop 0
	v_div_scale_f32 v34, s[4:5], v33, v33, 1.0
	v_rcp_f32_e32 v35, v34
	s_nop 0
	v_fma_f32 v38, -v34, v35, 1.0
	v_fmac_f32_e32 v35, v38, v35
	v_div_scale_f32 v38, vcc, 1.0, v33, 1.0
	v_mul_f32_e32 v39, v38, v35
	v_fma_f32 v40, -v34, v39, v38
	v_fmac_f32_e32 v39, v40, v35
	v_fma_f32 v34, -v34, v39, v38
	v_div_fmas_f32 v34, v34, v35, v39
	v_div_fixup_f32 v35, v34, v33, 1.0
	v_div_scale_f32 v33, s[4:5], v32, v32, 1.0
	v_rcp_f32_e32 v34, v33
	s_nop 0
	v_fma_f32 v38, -v33, v34, 1.0
	v_fmac_f32_e32 v34, v38, v34
	v_div_scale_f32 v38, vcc, 1.0, v32, 1.0
	v_mul_f32_e32 v39, v38, v34
	v_fma_f32 v40, -v33, v39, v38
	v_fmac_f32_e32 v39, v40, v34
	v_fma_f32 v33, -v33, v39, v38
	v_div_fmas_f32 v33, v33, v34, v39
	v_div_fixup_f32 v38, v33, v32, 1.0
	v_cvt_pk_bf16_f32 v32, v48, v49
	v_cvt_pk_bf16_f32 v33, v61, v60
	v_cvt_pk_bf16_f32 v34, v37, v36
	v_cvt_pk_bf16_f32 v35, v38, v35
	global_load_dwordx4 v[36:39], v[54:55], off offset:64
	s_waitcnt vmcnt(0)
	v_lshlrev_b32_e32 v50, 16, v36
	v_and_b32_e32 v51, 0xffff0000, v36
	v_lshlrev_b32_e32 v48, 16, v37
	v_and_b32_e32 v49, 0xffff0000, v37
	v_lshlrev_b32_e32 v46, 16, v38
	v_and_b32_e32 v47, 0xffff0000, v38
	v_lshlrev_b32_e32 v44, 16, v39
	v_and_b32_e32 v45, 0xffff0000, v39
	global_load_dwordx4 v[36:39], v[52:53], off offset:64
	s_waitcnt vmcnt(0)
	v_cndmask_b32_e64 v39, v39, 0, s[38:39]
	v_cndmask_b32_e64 v38, v38, 0, s[38:39]
	v_cndmask_b32_e64 v37, v37, 0, s[38:39]
	v_cndmask_b32_e64 v36, v36, 0, s[38:39]
	v_lshlrev_b32_e32 v72, 16, v36
	v_and_b32_e32 v73, 0xffff0000, v36
	v_lshlrev_b32_e32 v70, 16, v37
	v_and_b32_e32 v71, 0xffff0000, v37
	v_lshlrev_b32_e32 v60, 16, v38
	v_and_b32_e32 v61, 0xffff0000, v38
	v_lshlrev_b32_e32 v74, 16, v39
	v_and_b32_e32 v75, 0xffff0000, v39
	global_load_dwordx4 v[36:39], v[58:59], off offset:64
	v_sub_f32_e32 v73, v73, v51
	v_sub_f32_e32 v72, v72, v50
	v_sub_f32_e32 v71, v71, v49
	v_sub_f32_e32 v70, v70, v48
	s_waitcnt vmcnt(0)
	v_cndmask_b32_e64 v39, v39, 0, s[36:37]
	v_cndmask_b32_e64 v38, v38, 0, s[36:37]
	v_cndmask_b32_e64 v37, v37, 0, s[36:37]
	v_cndmask_b32_e64 v36, v36, 0, s[36:37]
	v_lshlrev_b32_e32 v76, 16, v36
	v_and_b32_e32 v77, 0xffff0000, v36
	v_lshlrev_b32_e32 v78, 16, v37
	v_and_b32_e32 v79, 0xffff0000, v37
	v_lshlrev_b32_e32 v80, 16, v38
	v_and_b32_e32 v81, 0xffff0000, v38
	v_lshlrev_b32_e32 v82, 16, v39
	v_and_b32_e32 v83, 0xffff0000, v39
	global_load_dwordx4 v[36:39], v[176:177], off offset:144
	global_load_dwordx4 v[62:65], v[176:177], off offset:128
	global_load_dwordx4 v[40:43], v[176:177], off offset:784
	global_load_dwordx4 v[66:69], v[176:177], off offset:768
	s_waitcnt vmcnt(2)
	v_pk_fma_f32 v[62:63], v[62:63], v[72:73], v[50:51]
	v_sub_f32_e32 v51, v77, v51
	v_sub_f32_e32 v50, v76, v50
	s_waitcnt vmcnt(0)
	v_pk_fma_f32 v[50:51], v[66:67], v[50:51], v[62:63]
	v_pk_fma_f32 v[64:65], v[64:65], v[70:71], v[48:49]
	v_mul_f32_e32 v50, 0xbfb8aa3b, v50
	v_mul_f32_e32 v51, 0xbfb8aa3b, v51
	v_exp_f32_e32 v50, v50
	v_exp_f32_e32 v51, v51
	v_sub_f32_e32 v49, v79, v49
	v_sub_f32_e32 v48, v78, v48
	v_pk_fma_f32 v[48:49], v[68:69], v[48:49], v[64:65]
	v_pk_add_f32 v[50:51], v[50:51], 1.0 op_sel_hi:[1,0]
	v_mul_f32_e32 v48, 0xbfb8aa3b, v48
	v_div_scale_f32 v62, s[4:5], v51, v51, 1.0
	v_rcp_f32_e32 v63, v62
	v_mul_f32_e32 v49, 0xbfb8aa3b, v49
	v_exp_f32_e32 v48, v48
	v_exp_f32_e32 v49, v49
	v_fma_f32 v64, -v62, v63, 1.0
	v_fmac_f32_e32 v63, v64, v63
	v_div_scale_f32 v64, vcc, 1.0, v51, 1.0
	v_mul_f32_e32 v65, v64, v63
	v_fma_f32 v66, -v62, v65, v64
	v_fmac_f32_e32 v65, v66, v63
	v_fma_f32 v62, -v62, v65, v64
	v_div_fmas_f32 v62, v62, v63, v65
	v_div_fixup_f32 v62, v62, v51, 1.0
	v_div_scale_f32 v51, s[4:5], v50, v50, 1.0
	v_rcp_f32_e32 v63, v51
	v_pk_add_f32 v[48:49], v[48:49], 1.0 op_sel_hi:[1,0]
	v_fma_f32 v64, -v51, v63, 1.0
	v_fmac_f32_e32 v63, v64, v63
	v_div_scale_f32 v64, vcc, 1.0, v50, 1.0
	v_mul_f32_e32 v65, v64, v63
	v_fma_f32 v66, -v51, v65, v64
	v_fmac_f32_e32 v65, v66, v63
	v_fma_f32 v51, -v51, v65, v64
	v_div_fmas_f32 v51, v51, v63, v65
	v_div_fixup_f32 v63, v51, v50, 1.0
	v_div_scale_f32 v50, s[4:5], v49, v49, 1.0
	v_rcp_f32_e32 v51, v50
	s_nop 0
	v_fma_f32 v64, -v50, v51, 1.0
	v_fmac_f32_e32 v51, v64, v51
	v_div_scale_f32 v64, vcc, 1.0, v49, 1.0
	v_mul_f32_e32 v65, v64, v51
	v_fma_f32 v66, -v50, v65, v64
	v_fmac_f32_e32 v65, v66, v51
	v_fma_f32 v50, -v50, v65, v64
	v_div_fmas_f32 v50, v50, v51, v65
	v_div_fixup_f32 v64, v50, v49, 1.0
	v_div_scale_f32 v49, s[4:5], v48, v48, 1.0
	v_rcp_f32_e32 v50, v49
	s_nop 0
	v_fma_f32 v51, -v49, v50, 1.0
	v_fmac_f32_e32 v50, v51, v50
	v_div_scale_f32 v51, vcc, 1.0, v48, 1.0
	v_mul_f32_e32 v65, v51, v50
	v_fma_f32 v66, -v49, v65, v51
	v_fmac_f32_e32 v65, v66, v50
	v_fma_f32 v49, -v49, v65, v51
	v_div_fmas_f32 v49, v49, v50, v65
	v_sub_f32_e32 v51, v61, v47
	v_sub_f32_e32 v50, v60, v46
	v_pk_fma_f32 v[36:37], v[36:37], v[50:51], v[46:47]
	v_sub_f32_e32 v47, v81, v47
	v_sub_f32_e32 v46, v80, v46
	v_pk_fma_f32 v[36:37], v[40:41], v[46:47], v[36:37]
	v_div_fixup_f32 v65, v49, v48, 1.0
	v_mul_f32_e32 v36, 0xbfb8aa3b, v36
	v_mul_f32_e32 v37, 0xbfb8aa3b, v37
	v_exp_f32_e32 v36, v36
	v_exp_f32_e32 v37, v37
	v_sub_f32_e32 v49, v75, v45
	v_sub_f32_e32 v48, v74, v44
	v_pk_fma_f32 v[38:39], v[38:39], v[48:49], v[44:45]
	v_pk_add_f32 v[36:37], v[36:37], 1.0 op_sel_hi:[1,0]
	v_sub_f32_e32 v45, v83, v45
	v_div_scale_f32 v40, s[4:5], v37, v37, 1.0
	v_rcp_f32_e32 v41, v40
	v_sub_f32_e32 v44, v82, v44
	v_pk_fma_f32 v[38:39], v[42:43], v[44:45], v[38:39]
	v_fma_f32 v42, -v40, v41, 1.0
	v_fmac_f32_e32 v41, v42, v41
	v_div_scale_f32 v42, vcc, 1.0, v37, 1.0
	v_mul_f32_e32 v43, v42, v41
	v_fma_f32 v44, -v40, v43, v42
	v_fmac_f32_e32 v43, v44, v41
	v_fma_f32 v40, -v40, v43, v42
	v_div_fmas_f32 v40, v40, v41, v43
	v_div_fixup_f32 v40, v40, v37, 1.0
	v_div_scale_f32 v37, s[4:5], v36, v36, 1.0
	v_rcp_f32_e32 v41, v37
	s_nop 0
	v_fma_f32 v42, -v37, v41, 1.0
	v_fmac_f32_e32 v41, v42, v41
	v_div_scale_f32 v42, vcc, 1.0, v36, 1.0
	v_mul_f32_e32 v43, v42, v41
	v_fma_f32 v44, -v37, v43, v42
	v_fmac_f32_e32 v43, v44, v41
	v_fma_f32 v37, -v37, v43, v42
	v_div_fmas_f32 v37, v37, v41, v43
	v_div_fixup_f32 v41, v37, v36, 1.0
	v_mul_f32_e32 v36, 0xbfb8aa3b, v38
	v_mul_f32_e32 v37, 0xbfb8aa3b, v39
	v_exp_f32_e32 v36, v36
	v_exp_f32_e32 v37, v37
	s_nop 0
	v_pk_add_f32 v[36:37], v[36:37], 1.0 op_sel_hi:[1,0]
	s_nop 0
	v_div_scale_f32 v38, s[4:5], v37, v37, 1.0
	v_rcp_f32_e32 v39, v38
	s_nop 0
	v_fma_f32 v42, -v38, v39, 1.0
	v_fmac_f32_e32 v39, v42, v39
	v_div_scale_f32 v42, vcc, 1.0, v37, 1.0
	v_mul_f32_e32 v43, v42, v39
	v_fma_f32 v44, -v38, v43, v42
	v_fmac_f32_e32 v43, v44, v39
	v_fma_f32 v38, -v38, v43, v42
	v_div_fmas_f32 v38, v38, v39, v43
	v_div_fixup_f32 v39, v38, v37, 1.0
	v_div_scale_f32 v37, s[4:5], v36, v36, 1.0
	v_rcp_f32_e32 v38, v37
	s_nop 0
	v_fma_f32 v42, -v37, v38, 1.0
	v_fmac_f32_e32 v38, v42, v38
	v_div_scale_f32 v42, vcc, 1.0, v36, 1.0
	v_mul_f32_e32 v43, v42, v38
	v_fma_f32 v44, -v37, v43, v42
	v_fmac_f32_e32 v43, v44, v38
	v_fma_f32 v37, -v37, v43, v42
	v_div_fmas_f32 v37, v37, v38, v43
	v_div_fixup_f32 v42, v37, v36, 1.0
	v_cvt_pk_bf16_f32 v36, v63, v62
	v_cvt_pk_bf16_f32 v37, v65, v64
	v_cvt_pk_bf16_f32 v38, v41, v40
	v_cvt_pk_bf16_f32 v39, v42, v39
	global_load_dwordx4 v[40:43], v[54:55], off offset:128
	s_waitcnt vmcnt(0)
	v_lshlrev_b32_e32 v62, 16, v40
	v_and_b32_e32 v63, 0xffff0000, v40
	v_lshlrev_b32_e32 v60, 16, v41
	v_and_b32_e32 v61, 0xffff0000, v41
	v_lshlrev_b32_e32 v50, 16, v42
	v_and_b32_e32 v51, 0xffff0000, v42
	v_lshlrev_b32_e32 v48, 16, v43
	v_and_b32_e32 v49, 0xffff0000, v43
	global_load_dwordx4 v[40:43], v[52:53], off offset:128
	s_waitcnt vmcnt(0)
	v_cndmask_b32_e64 v43, v43, 0, s[38:39]
	v_cndmask_b32_e64 v42, v42, 0, s[38:39]
	v_cndmask_b32_e64 v41, v41, 0, s[38:39]
	v_cndmask_b32_e64 v40, v40, 0, s[38:39]
	v_lshlrev_b32_e32 v76, 16, v40
	v_and_b32_e32 v77, 0xffff0000, v40
	v_lshlrev_b32_e32 v74, 16, v41
	v_and_b32_e32 v75, 0xffff0000, v41
	v_lshlrev_b32_e32 v64, 16, v42
	v_and_b32_e32 v65, 0xffff0000, v42
	v_lshlrev_b32_e32 v78, 16, v43
	v_and_b32_e32 v79, 0xffff0000, v43
	global_load_dwordx4 v[40:43], v[58:59], off offset:128
	v_sub_f32_e32 v77, v77, v63
	v_sub_f32_e32 v76, v76, v62
	v_sub_f32_e32 v75, v75, v61
	v_sub_f32_e32 v74, v74, v60
	s_waitcnt vmcnt(0)
	v_cndmask_b32_e64 v43, v43, 0, s[36:37]
	v_cndmask_b32_e64 v42, v42, 0, s[36:37]
	v_cndmask_b32_e64 v41, v41, 0, s[36:37]
	v_cndmask_b32_e64 v40, v40, 0, s[36:37]
	v_lshlrev_b32_e32 v80, 16, v40
	v_and_b32_e32 v81, 0xffff0000, v40
	v_lshlrev_b32_e32 v82, 16, v41
	v_and_b32_e32 v83, 0xffff0000, v41
	v_lshlrev_b32_e32 v84, 16, v42
	v_and_b32_e32 v85, 0xffff0000, v42
	v_lshlrev_b32_e32 v86, 16, v43
	v_and_b32_e32 v87, 0xffff0000, v43
	global_load_dwordx4 v[40:43], v[176:177], off offset:272
	global_load_dwordx4 v[66:69], v[176:177], off offset:256
	global_load_dwordx4 v[44:47], v[176:177], off offset:912
	global_load_dwordx4 v[70:73], v[176:177], off offset:896
	s_waitcnt vmcnt(2)
	v_pk_fma_f32 v[66:67], v[66:67], v[76:77], v[62:63]
	v_sub_f32_e32 v63, v81, v63
	v_sub_f32_e32 v62, v80, v62
	s_waitcnt vmcnt(0)
	v_pk_fma_f32 v[62:63], v[70:71], v[62:63], v[66:67]
	v_pk_fma_f32 v[68:69], v[68:69], v[74:75], v[60:61]
	v_mul_f32_e32 v62, 0xbfb8aa3b, v62
	v_mul_f32_e32 v63, 0xbfb8aa3b, v63
	v_exp_f32_e32 v62, v62
	v_exp_f32_e32 v63, v63
	v_sub_f32_e32 v61, v83, v61
	v_sub_f32_e32 v60, v82, v60
	v_pk_fma_f32 v[60:61], v[72:73], v[60:61], v[68:69]
	v_pk_add_f32 v[62:63], v[62:63], 1.0 op_sel_hi:[1,0]
	v_mul_f32_e32 v60, 0xbfb8aa3b, v60
	v_div_scale_f32 v66, s[4:5], v63, v63, 1.0
	v_rcp_f32_e32 v67, v66
	v_mul_f32_e32 v61, 0xbfb8aa3b, v61
	v_exp_f32_e32 v60, v60
	v_exp_f32_e32 v61, v61
	v_fma_f32 v68, -v66, v67, 1.0
	v_fmac_f32_e32 v67, v68, v67
	v_div_scale_f32 v68, vcc, 1.0, v63, 1.0
	v_mul_f32_e32 v69, v68, v67
	v_fma_f32 v70, -v66, v69, v68
	v_fmac_f32_e32 v69, v70, v67
	v_fma_f32 v66, -v66, v69, v68
	v_div_fmas_f32 v66, v66, v67, v69
	v_div_fixup_f32 v66, v66, v63, 1.0
	v_div_scale_f32 v63, s[4:5], v62, v62, 1.0
	v_rcp_f32_e32 v67, v63
	v_pk_add_f32 v[60:61], v[60:61], 1.0 op_sel_hi:[1,0]
	v_fma_f32 v68, -v63, v67, 1.0
	v_fmac_f32_e32 v67, v68, v67
	v_div_scale_f32 v68, vcc, 1.0, v62, 1.0
	v_mul_f32_e32 v69, v68, v67
	v_fma_f32 v70, -v63, v69, v68
	v_fmac_f32_e32 v69, v70, v67
	v_fma_f32 v63, -v63, v69, v68
	v_div_fmas_f32 v63, v63, v67, v69
	v_div_fixup_f32 v67, v63, v62, 1.0
	v_div_scale_f32 v62, s[4:5], v61, v61, 1.0
	v_rcp_f32_e32 v63, v62
	s_nop 0
	v_fma_f32 v68, -v62, v63, 1.0
	v_fmac_f32_e32 v63, v68, v63
	v_div_scale_f32 v68, vcc, 1.0, v61, 1.0
	v_mul_f32_e32 v69, v68, v63
	v_fma_f32 v70, -v62, v69, v68
	v_fmac_f32_e32 v69, v70, v63
	v_fma_f32 v62, -v62, v69, v68
	v_div_fmas_f32 v62, v62, v63, v69
	v_div_fixup_f32 v68, v62, v61, 1.0
	v_div_scale_f32 v61, s[4:5], v60, v60, 1.0
	v_rcp_f32_e32 v62, v61
	s_nop 0
	v_fma_f32 v63, -v61, v62, 1.0
	v_fmac_f32_e32 v62, v63, v62
	v_div_scale_f32 v63, vcc, 1.0, v60, 1.0
	v_mul_f32_e32 v69, v63, v62
	v_fma_f32 v70, -v61, v69, v63
	v_fmac_f32_e32 v69, v70, v62
	v_fma_f32 v61, -v61, v69, v63
	v_div_fmas_f32 v61, v61, v62, v69
	v_sub_f32_e32 v63, v65, v51
	v_sub_f32_e32 v62, v64, v50
	v_pk_fma_f32 v[40:41], v[40:41], v[62:63], v[50:51]
	v_sub_f32_e32 v51, v85, v51
	v_sub_f32_e32 v50, v84, v50
	v_pk_fma_f32 v[40:41], v[44:45], v[50:51], v[40:41]
	v_div_fixup_f32 v69, v61, v60, 1.0
	v_mul_f32_e32 v40, 0xbfb8aa3b, v40
	v_mul_f32_e32 v41, 0xbfb8aa3b, v41
	v_exp_f32_e32 v40, v40
	v_exp_f32_e32 v41, v41
	v_sub_f32_e32 v61, v79, v49
	v_sub_f32_e32 v60, v78, v48
	v_pk_fma_f32 v[42:43], v[42:43], v[60:61], v[48:49]
	v_pk_add_f32 v[40:41], v[40:41], 1.0 op_sel_hi:[1,0]
	v_sub_f32_e32 v49, v87, v49
	v_div_scale_f32 v44, s[4:5], v41, v41, 1.0
	v_rcp_f32_e32 v45, v44
	v_sub_f32_e32 v48, v86, v48
	v_pk_fma_f32 v[42:43], v[46:47], v[48:49], v[42:43]
	v_fma_f32 v46, -v44, v45, 1.0
	v_fmac_f32_e32 v45, v46, v45
	v_div_scale_f32 v46, vcc, 1.0, v41, 1.0
	v_mul_f32_e32 v47, v46, v45
	v_fma_f32 v48, -v44, v47, v46
	v_fmac_f32_e32 v47, v48, v45
	v_fma_f32 v44, -v44, v47, v46
	v_div_fmas_f32 v44, v44, v45, v47
	v_div_fixup_f32 v44, v44, v41, 1.0
	v_div_scale_f32 v41, s[4:5], v40, v40, 1.0
	v_rcp_f32_e32 v45, v41
	s_nop 0
	v_fma_f32 v46, -v41, v45, 1.0
	v_fmac_f32_e32 v45, v46, v45
	v_div_scale_f32 v46, vcc, 1.0, v40, 1.0
	v_mul_f32_e32 v47, v46, v45
	v_fma_f32 v48, -v41, v47, v46
	v_fmac_f32_e32 v47, v48, v45
	v_fma_f32 v41, -v41, v47, v46
	v_div_fmas_f32 v41, v41, v45, v47
	v_div_fixup_f32 v45, v41, v40, 1.0
	v_mul_f32_e32 v40, 0xbfb8aa3b, v42
	v_mul_f32_e32 v41, 0xbfb8aa3b, v43
	v_exp_f32_e32 v40, v40
	v_exp_f32_e32 v41, v41
	s_nop 0
	v_pk_add_f32 v[40:41], v[40:41], 1.0 op_sel_hi:[1,0]
	s_nop 0
	v_div_scale_f32 v42, s[4:5], v41, v41, 1.0
	v_rcp_f32_e32 v43, v42
	s_nop 0
	v_fma_f32 v46, -v42, v43, 1.0
	v_fmac_f32_e32 v43, v46, v43
	v_div_scale_f32 v46, vcc, 1.0, v41, 1.0
	v_mul_f32_e32 v47, v46, v43
	v_fma_f32 v48, -v42, v47, v46
	v_fmac_f32_e32 v47, v48, v43
	v_fma_f32 v42, -v42, v47, v46
	v_div_fmas_f32 v42, v42, v43, v47
	v_div_fixup_f32 v43, v42, v41, 1.0
	v_div_scale_f32 v41, s[4:5], v40, v40, 1.0
	v_rcp_f32_e32 v42, v41
	s_nop 0
	v_fma_f32 v46, -v41, v42, 1.0
	v_fmac_f32_e32 v42, v46, v42
	v_div_scale_f32 v46, vcc, 1.0, v40, 1.0
	v_mul_f32_e32 v47, v46, v42
	v_fma_f32 v48, -v41, v47, v46
	v_fmac_f32_e32 v47, v48, v42
	v_fma_f32 v41, -v41, v47, v46
	v_div_fmas_f32 v41, v41, v42, v47
	v_div_fixup_f32 v46, v41, v40, 1.0
	v_cvt_pk_bf16_f32 v40, v67, v66
	v_cvt_pk_bf16_f32 v41, v69, v68
	v_cvt_pk_bf16_f32 v42, v45, v44
	v_cvt_pk_bf16_f32 v43, v46, v43
	global_load_dwordx4 v[44:47], v[54:55], off offset:192
	s_waitcnt vmcnt(0)
	v_lshlrev_b32_e32 v66, 16, v44
	v_and_b32_e32 v67, 0xffff0000, v44
	v_lshlrev_b32_e32 v64, 16, v45
	v_and_b32_e32 v65, 0xffff0000, v45
	v_lshlrev_b32_e32 v62, 16, v46
	v_and_b32_e32 v63, 0xffff0000, v46
	v_lshlrev_b32_e32 v60, 16, v47
	v_and_b32_e32 v61, 0xffff0000, v47
	global_load_dwordx4 v[44:47], v[52:53], off offset:192
	s_waitcnt vmcnt(0)
	v_cndmask_b32_e64 v47, v47, 0, s[38:39]
	v_cndmask_b32_e64 v46, v46, 0, s[38:39]
	v_cndmask_b32_e64 v45, v45, 0, s[38:39]
	v_cndmask_b32_e64 v44, v44, 0, s[38:39]
	v_lshlrev_b32_e32 v80, 16, v44
	v_and_b32_e32 v81, 0xffff0000, v44
	v_lshlrev_b32_e32 v78, 16, v45
	v_and_b32_e32 v79, 0xffff0000, v45
	v_lshlrev_b32_e32 v68, 16, v46
	v_and_b32_e32 v69, 0xffff0000, v46
	v_lshlrev_b32_e32 v82, 16, v47
	v_and_b32_e32 v83, 0xffff0000, v47
	global_load_dwordx4 v[44:47], v[58:59], off offset:192
	v_sub_f32_e32 v81, v81, v67
	v_sub_f32_e32 v80, v80, v66
	v_sub_f32_e32 v79, v79, v65
	v_sub_f32_e32 v78, v78, v64
	s_waitcnt vmcnt(0)
	v_cndmask_b32_e64 v47, v47, 0, s[36:37]
	v_cndmask_b32_e64 v46, v46, 0, s[36:37]
	v_cndmask_b32_e64 v45, v45, 0, s[36:37]
	v_cndmask_b32_e64 v44, v44, 0, s[36:37]
	v_lshlrev_b32_e32 v84, 16, v44
	v_and_b32_e32 v85, 0xffff0000, v44
	v_lshlrev_b32_e32 v86, 16, v45
	v_and_b32_e32 v87, 0xffff0000, v45
	v_lshlrev_b32_e32 v88, 16, v46
	v_and_b32_e32 v89, 0xffff0000, v46
	v_lshlrev_b32_e32 v90, 16, v47
	v_and_b32_e32 v91, 0xffff0000, v47
	global_load_dwordx4 v[44:47], v[176:177], off offset:400
	global_load_dwordx4 v[70:73], v[176:177], off offset:384
	global_load_dwordx4 v[48:51], v[176:177], off offset:1040
	global_load_dwordx4 v[74:77], v[176:177], off offset:1024
	s_waitcnt vmcnt(2)
	v_pk_fma_f32 v[70:71], v[70:71], v[80:81], v[66:67]
	v_sub_f32_e32 v67, v85, v67
	v_sub_f32_e32 v66, v84, v66
	s_waitcnt vmcnt(0)
	v_pk_fma_f32 v[66:67], v[74:75], v[66:67], v[70:71]
	v_pk_fma_f32 v[72:73], v[72:73], v[78:79], v[64:65]
	v_mul_f32_e32 v66, 0xbfb8aa3b, v66
	v_mul_f32_e32 v67, 0xbfb8aa3b, v67
	v_exp_f32_e32 v66, v66
	v_exp_f32_e32 v67, v67
	v_sub_f32_e32 v65, v87, v65
	v_sub_f32_e32 v64, v86, v64
	v_pk_fma_f32 v[64:65], v[76:77], v[64:65], v[72:73]
	v_pk_add_f32 v[66:67], v[66:67], 1.0 op_sel_hi:[1,0]
	v_mul_f32_e32 v64, 0xbfb8aa3b, v64
	v_div_scale_f32 v70, s[4:5], v67, v67, 1.0
	v_rcp_f32_e32 v71, v70
	v_mul_f32_e32 v65, 0xbfb8aa3b, v65
	v_exp_f32_e32 v64, v64
	v_exp_f32_e32 v65, v65
	v_fma_f32 v72, -v70, v71, 1.0
	v_fmac_f32_e32 v71, v72, v71
	v_div_scale_f32 v72, vcc, 1.0, v67, 1.0
	v_mul_f32_e32 v73, v72, v71
	v_fma_f32 v74, -v70, v73, v72
	v_fmac_f32_e32 v73, v74, v71
	v_fma_f32 v70, -v70, v73, v72
	v_div_fmas_f32 v70, v70, v71, v73
	v_div_fixup_f32 v70, v70, v67, 1.0
	v_div_scale_f32 v67, s[4:5], v66, v66, 1.0
	v_rcp_f32_e32 v71, v67
	v_pk_add_f32 v[64:65], v[64:65], 1.0 op_sel_hi:[1,0]
	v_fma_f32 v72, -v67, v71, 1.0
	v_fmac_f32_e32 v71, v72, v71
	v_div_scale_f32 v72, vcc, 1.0, v66, 1.0
	v_mul_f32_e32 v73, v72, v71
	v_fma_f32 v74, -v67, v73, v72
	v_fmac_f32_e32 v73, v74, v71
	v_fma_f32 v67, -v67, v73, v72
	v_div_fmas_f32 v67, v67, v71, v73
	v_div_fixup_f32 v71, v67, v66, 1.0
	v_div_scale_f32 v66, s[4:5], v65, v65, 1.0
	v_rcp_f32_e32 v67, v66
	s_nop 0
	v_fma_f32 v72, -v66, v67, 1.0
	v_fmac_f32_e32 v67, v72, v67
	v_div_scale_f32 v72, vcc, 1.0, v65, 1.0
	v_mul_f32_e32 v73, v72, v67
	v_fma_f32 v74, -v66, v73, v72
	v_fmac_f32_e32 v73, v74, v67
	v_fma_f32 v66, -v66, v73, v72
	v_div_fmas_f32 v66, v66, v67, v73
	v_div_fixup_f32 v72, v66, v65, 1.0
	v_div_scale_f32 v65, s[4:5], v64, v64, 1.0
	v_rcp_f32_e32 v66, v65
	s_nop 0
	v_fma_f32 v67, -v65, v66, 1.0
	v_fmac_f32_e32 v66, v67, v66
	v_div_scale_f32 v67, vcc, 1.0, v64, 1.0
	v_mul_f32_e32 v73, v67, v66
	v_fma_f32 v74, -v65, v73, v67
	v_fmac_f32_e32 v73, v74, v66
	v_fma_f32 v65, -v65, v73, v67
	v_div_fmas_f32 v65, v65, v66, v73
	v_sub_f32_e32 v67, v69, v63
	v_sub_f32_e32 v66, v68, v62
	v_pk_fma_f32 v[44:45], v[44:45], v[66:67], v[62:63]
	v_sub_f32_e32 v63, v89, v63
	v_sub_f32_e32 v62, v88, v62
	v_pk_fma_f32 v[44:45], v[48:49], v[62:63], v[44:45]
	v_div_fixup_f32 v73, v65, v64, 1.0
	v_mul_f32_e32 v44, 0xbfb8aa3b, v44
	v_mul_f32_e32 v45, 0xbfb8aa3b, v45
	v_exp_f32_e32 v44, v44
	v_exp_f32_e32 v45, v45
	v_sub_f32_e32 v65, v83, v61
	v_sub_f32_e32 v64, v82, v60
	v_pk_fma_f32 v[46:47], v[46:47], v[64:65], v[60:61]
	v_pk_add_f32 v[44:45], v[44:45], 1.0 op_sel_hi:[1,0]
	v_sub_f32_e32 v61, v91, v61
	v_div_scale_f32 v48, s[4:5], v45, v45, 1.0
	v_rcp_f32_e32 v49, v48
	v_sub_f32_e32 v60, v90, v60
	v_pk_fma_f32 v[46:47], v[50:51], v[60:61], v[46:47]
	v_fma_f32 v50, -v48, v49, 1.0
	v_fmac_f32_e32 v49, v50, v49
	v_div_scale_f32 v50, vcc, 1.0, v45, 1.0
	v_mul_f32_e32 v51, v50, v49
	v_fma_f32 v60, -v48, v51, v50
	v_fmac_f32_e32 v51, v60, v49
	v_fma_f32 v48, -v48, v51, v50
	v_div_fmas_f32 v48, v48, v49, v51
	v_div_fixup_f32 v48, v48, v45, 1.0
	v_div_scale_f32 v45, s[4:5], v44, v44, 1.0
	v_rcp_f32_e32 v49, v45
	s_nop 0
	v_fma_f32 v50, -v45, v49, 1.0
	v_fmac_f32_e32 v49, v50, v49
	v_div_scale_f32 v50, vcc, 1.0, v44, 1.0
	v_mul_f32_e32 v51, v50, v49
	v_fma_f32 v60, -v45, v51, v50
	v_fmac_f32_e32 v51, v60, v49
	v_fma_f32 v45, -v45, v51, v50
	v_div_fmas_f32 v45, v45, v49, v51
	v_div_fixup_f32 v49, v45, v44, 1.0
	v_mul_f32_e32 v44, 0xbfb8aa3b, v46
	v_mul_f32_e32 v45, 0xbfb8aa3b, v47
	v_exp_f32_e32 v44, v44
	v_exp_f32_e32 v45, v45
	s_nop 0
	v_pk_add_f32 v[44:45], v[44:45], 1.0 op_sel_hi:[1,0]
	s_nop 0
	v_div_scale_f32 v46, s[4:5], v45, v45, 1.0
	v_rcp_f32_e32 v47, v46
	s_nop 0
	v_fma_f32 v50, -v46, v47, 1.0
	v_fmac_f32_e32 v47, v50, v47
	v_div_scale_f32 v50, vcc, 1.0, v45, 1.0
	v_mul_f32_e32 v51, v50, v47
	v_fma_f32 v60, -v46, v51, v50
	v_fmac_f32_e32 v51, v60, v47
	v_fma_f32 v46, -v46, v51, v50
	v_div_fmas_f32 v46, v46, v47, v51
	v_div_fixup_f32 v47, v46, v45, 1.0
	v_div_scale_f32 v45, s[4:5], v44, v44, 1.0
	v_rcp_f32_e32 v46, v45
	s_nop 0
	v_fma_f32 v50, -v45, v46, 1.0
	v_fmac_f32_e32 v46, v50, v46
	v_div_scale_f32 v50, vcc, 1.0, v44, 1.0
	v_mul_f32_e32 v51, v50, v46
	v_fma_f32 v60, -v45, v51, v50
	v_fmac_f32_e32 v51, v60, v46
	v_fma_f32 v45, -v45, v51, v50
	v_div_fmas_f32 v45, v45, v46, v51
	v_div_fixup_f32 v50, v45, v44, 1.0
	v_cvt_pk_bf16_f32 v44, v71, v70
	v_cvt_pk_bf16_f32 v45, v73, v72
	v_cvt_pk_bf16_f32 v46, v49, v48
	v_cvt_pk_bf16_f32 v47, v50, v47
	global_load_dwordx4 v[48:51], v[54:55], off offset:256
	s_waitcnt vmcnt(0)
	v_lshlrev_b32_e32 v66, 16, v48
	v_and_b32_e32 v67, 0xffff0000, v48
	v_lshlrev_b32_e32 v64, 16, v49
	v_and_b32_e32 v65, 0xffff0000, v49
	v_lshlrev_b32_e32 v62, 16, v50
	v_and_b32_e32 v63, 0xffff0000, v50
	v_lshlrev_b32_e32 v60, 16, v51
	v_and_b32_e32 v61, 0xffff0000, v51
	global_load_dwordx4 v[48:51], v[52:53], off offset:256
	s_waitcnt vmcnt(0)
	v_cndmask_b32_e64 v51, v51, 0, s[38:39]
	v_cndmask_b32_e64 v50, v50, 0, s[38:39]
	v_cndmask_b32_e64 v49, v49, 0, s[38:39]
	v_cndmask_b32_e64 v48, v48, 0, s[38:39]
	v_lshlrev_b32_e32 v78, 16, v48
	v_and_b32_e32 v79, 0xffff0000, v48
	v_lshlrev_b32_e32 v80, 16, v49
	v_and_b32_e32 v81, 0xffff0000, v49
	v_lshlrev_b32_e32 v68, 16, v50
	v_and_b32_e32 v69, 0xffff0000, v50
	v_lshlrev_b32_e32 v82, 16, v51
	v_and_b32_e32 v83, 0xffff0000, v51
	global_load_dwordx4 v[48:51], v[58:59], off offset:256
	v_sub_f32_e32 v59, v81, v65
	v_sub_f32_e32 v58, v80, v64
	v_sub_f32_e32 v79, v79, v67
	v_sub_f32_e32 v78, v78, v66
	s_waitcnt vmcnt(0)
	v_cndmask_b32_e64 v51, v51, 0, s[36:37]
	v_cndmask_b32_e64 v50, v50, 0, s[36:37]
	v_cndmask_b32_e64 v49, v49, 0, s[36:37]
	v_cndmask_b32_e64 v48, v48, 0, s[36:37]
	v_lshlrev_b32_e32 v84, 16, v48
	v_and_b32_e32 v85, 0xffff0000, v48
	v_lshlrev_b32_e32 v86, 16, v49
	v_and_b32_e32 v87, 0xffff0000, v49
	v_lshlrev_b32_e32 v88, 16, v50
	v_and_b32_e32 v89, 0xffff0000, v50
	v_lshlrev_b32_e32 v90, 16, v51
	v_and_b32_e32 v91, 0xffff0000, v51
	global_load_dwordx4 v[48:51], v[176:177], off offset:528
	global_load_dwordx4 v[70:73], v[176:177], off offset:512
	global_load_dwordx4 v[52:55], v[176:177], off offset:1168
	global_load_dwordx4 v[74:77], v[176:177], off offset:1152
	s_waitcnt vmcnt(2)
	v_pk_fma_f32 v[70:71], v[70:71], v[78:79], v[66:67]
	v_pk_fma_f32 v[58:59], v[72:73], v[58:59], v[64:65]
	v_sub_f32_e32 v67, v85, v67
	v_sub_f32_e32 v66, v84, v66
	v_sub_f32_e32 v65, v87, v65
	v_sub_f32_e32 v64, v86, v64
	s_waitcnt vmcnt(0)
	v_pk_fma_f32 v[58:59], v[76:77], v[64:65], v[58:59]
	v_pk_fma_f32 v[64:65], v[74:75], v[66:67], v[70:71]
	v_mul_f32_e32 v58, 0xbfb8aa3b, v58
	v_mul_f32_e32 v64, 0xbfb8aa3b, v64
	v_mul_f32_e32 v65, 0xbfb8aa3b, v65
	v_exp_f32_e32 v64, v64
	v_exp_f32_e32 v65, v65
	v_mul_f32_e32 v59, 0xbfb8aa3b, v59
	v_exp_f32_e32 v58, v58
	v_exp_f32_e32 v59, v59
	v_pk_add_f32 v[64:65], v[64:65], 1.0 op_sel_hi:[1,0]
	v_pk_add_f32 v[58:59], v[58:59], 1.0 op_sel_hi:[1,0]
	v_div_scale_f32 v66, s[4:5], v65, v65, 1.0
	v_rcp_f32_e32 v67, v66
	s_nop 0
	v_fma_f32 v70, -v66, v67, 1.0
	v_fmac_f32_e32 v67, v70, v67
	v_div_scale_f32 v70, vcc, 1.0, v65, 1.0
	v_mul_f32_e32 v71, v70, v67
	v_fma_f32 v72, -v66, v71, v70
	v_fmac_f32_e32 v71, v72, v67
	v_fma_f32 v66, -v66, v71, v70
	v_div_fmas_f32 v66, v66, v67, v71
	v_div_fixup_f32 v66, v66, v65, 1.0
	v_div_scale_f32 v65, s[4:5], v64, v64, 1.0
	v_rcp_f32_e32 v67, v65
	s_nop 0
	v_fma_f32 v70, -v65, v67, 1.0
	v_fmac_f32_e32 v67, v70, v67
	v_div_scale_f32 v70, vcc, 1.0, v64, 1.0
	v_mul_f32_e32 v71, v70, v67
	v_fma_f32 v72, -v65, v71, v70
	v_fmac_f32_e32 v71, v72, v67
	v_fma_f32 v65, -v65, v71, v70
	v_div_fmas_f32 v65, v65, v67, v71
	v_div_fixup_f32 v67, v65, v64, 1.0
	v_div_scale_f32 v64, s[4:5], v59, v59, 1.0
	v_rcp_f32_e32 v65, v64
	s_nop 0
	v_fma_f32 v70, -v64, v65, 1.0
	v_fmac_f32_e32 v65, v70, v65
	v_div_scale_f32 v70, vcc, 1.0, v59, 1.0
	v_mul_f32_e32 v71, v70, v65
	v_fma_f32 v72, -v64, v71, v70
	v_fmac_f32_e32 v71, v72, v65
	v_fma_f32 v64, -v64, v71, v70
	v_div_fmas_f32 v64, v64, v65, v71
	v_div_fixup_f32 v70, v64, v59, 1.0
	v_div_scale_f32 v59, s[4:5], v58, v58, 1.0
	v_rcp_f32_e32 v64, v59
	s_nop 0
	v_fma_f32 v65, -v59, v64, 1.0
	v_fmac_f32_e32 v64, v65, v64
	v_div_scale_f32 v65, vcc, 1.0, v58, 1.0
	v_mul_f32_e32 v71, v65, v64
	v_fma_f32 v72, -v59, v71, v65
	v_fmac_f32_e32 v71, v72, v64
	v_fma_f32 v59, -v59, v71, v65
	v_div_fmas_f32 v59, v59, v64, v71
	v_div_fixup_f32 v71, v59, v58, 1.0
	v_sub_f32_e32 v59, v83, v61
	v_sub_f32_e32 v58, v82, v60
	v_sub_f32_e32 v65, v69, v63
	v_sub_f32_e32 v64, v68, v62
	v_pk_fma_f32 v[48:49], v[48:49], v[64:65], v[62:63]
	v_pk_fma_f32 v[50:51], v[50:51], v[58:59], v[60:61]
	v_sub_f32_e32 v59, v89, v63
	v_sub_f32_e32 v58, v88, v62
	v_pk_fma_f32 v[48:49], v[52:53], v[58:59], v[48:49]
	v_sub_f32_e32 v61, v91, v61
	v_mul_f32_e32 v48, 0xbfb8aa3b, v48
	v_mul_f32_e32 v49, 0xbfb8aa3b, v49
	v_exp_f32_e32 v48, v48
	v_exp_f32_e32 v49, v49
	v_sub_f32_e32 v60, v90, v60
	v_pk_fma_f32 v[50:51], v[54:55], v[60:61], v[50:51]
	v_pk_add_f32 v[48:49], v[48:49], 1.0 op_sel_hi:[1,0]
	s_nop 0
	v_div_scale_f32 v52, s[4:5], v49, v49, 1.0
	v_rcp_f32_e32 v53, v52
	s_nop 0
	v_fma_f32 v54, -v52, v53, 1.0
	v_fmac_f32_e32 v53, v54, v53
	v_div_scale_f32 v54, vcc, 1.0, v49, 1.0
	v_mul_f32_e32 v55, v54, v53
	v_fma_f32 v58, -v52, v55, v54
	v_fmac_f32_e32 v55, v58, v53
	v_fma_f32 v52, -v52, v55, v54
	v_div_fmas_f32 v52, v52, v53, v55
	v_div_fixup_f32 v52, v52, v49, 1.0
	v_div_scale_f32 v49, s[4:5], v48, v48, 1.0
	v_rcp_f32_e32 v53, v49
	s_nop 0
	v_fma_f32 v54, -v49, v53, 1.0
	v_fmac_f32_e32 v53, v54, v53
	v_div_scale_f32 v54, vcc, 1.0, v48, 1.0
	v_mul_f32_e32 v55, v54, v53
	v_fma_f32 v58, -v49, v55, v54
	v_fmac_f32_e32 v55, v58, v53
	v_fma_f32 v49, -v49, v55, v54
	v_div_fmas_f32 v49, v49, v53, v55
	v_div_fixup_f32 v53, v49, v48, 1.0
	v_mul_f32_e32 v48, 0xbfb8aa3b, v50
	v_mul_f32_e32 v49, 0xbfb8aa3b, v51
	v_exp_f32_e32 v48, v48
	v_exp_f32_e32 v49, v49
	s_nop 0
	v_pk_add_f32 v[48:49], v[48:49], 1.0 op_sel_hi:[1,0]
	s_nop 0
	v_div_scale_f32 v50, s[4:5], v49, v49, 1.0
	v_rcp_f32_e32 v51, v50
	s_nop 0
	v_fma_f32 v54, -v50, v51, 1.0
	v_fmac_f32_e32 v51, v54, v51
	v_div_scale_f32 v54, vcc, 1.0, v49, 1.0
	v_mul_f32_e32 v55, v54, v51
	v_fma_f32 v58, -v50, v55, v54
	v_fmac_f32_e32 v55, v58, v51
	v_fma_f32 v50, -v50, v55, v54
	v_div_fmas_f32 v50, v50, v51, v55
	v_div_fixup_f32 v51, v50, v49, 1.0
	v_div_scale_f32 v49, s[4:5], v48, v48, 1.0
	v_rcp_f32_e32 v50, v49
	s_lshl_b32 s4, s10, 6
	s_or_b32 s6, s2, s4
	v_add_u32_e32 v190, s6, v164
	v_fma_f32 v54, -v49, v50, 1.0
	v_fmac_f32_e32 v50, v54, v50
	v_div_scale_f32 v54, vcc, 1.0, v48, 1.0
	v_mul_f32_e32 v55, v54, v50
	v_fma_f32 v58, -v49, v55, v54
	v_fmac_f32_e32 v55, v58, v50
	v_fma_f32 v49, -v49, v55, v54
	v_div_fmas_f32 v49, v49, v50, v55
	v_div_fixup_f32 v54, v49, v48, 1.0
	v_or_b32_e32 v58, s6, v227
	v_cvt_pk_bf16_f32 v48, v67, v66
	v_cvt_pk_bf16_f32 v49, v71, v70
	v_cvt_pk_bf16_f32 v50, v53, v52
	v_cvt_pk_bf16_f32 v51, v54, v51
	v_lshlrev_b32_e32 v208, 7, v58
	v_ashrrev_i32_e32 v191, 31, v190
	v_lshl_add_u64 v[54:55], v[168:169], 0, v[208:209]
	v_lshl_add_u64 v[52:53], v[190:191], 2, s[42:43]
	global_load_dwordx4 v[76:79], v[54:55], off
	global_load_dwordx4 v[80:83], v[54:55], off offset:64
	global_load_dwordx4 v[68:71], v[52:53], off offset:48
	global_load_dwordx4 v[72:75], v[52:53], off offset:32
	global_load_dwordx4 v[84:87], v[52:53], off offset:16
	global_load_dwordx4 v[96:99], v[52:53], off
	global_load_dwordx4 v[88:91], v[54:55], off offset:512
	global_load_dwordx4 v[92:95], v[54:55], off offset:576
	global_load_dwordx4 v[100:103], v[54:55], off offset:1024
	global_load_dwordx4 v[104:107], v[54:55], off offset:1088
	global_load_dwordx4 v[108:111], v[54:55], off offset:1536
	global_load_dwordx4 v[112:115], v[54:55], off offset:1600
	v_lshlrev_b64 v[52:53], 11, v[56:57]
	v_lshl_add_u64 v[192:193], s[52:53], 0, v[52:53]
	v_lshl_add_u64 v[52:53], v[178:179], 0, v[52:53]
	s_lshl_b32 s24, s6, 1
	v_lshl_add_u64 v[194:195], v[52:53], 0, s[24:25]
	v_or_b32_e32 v52, s6, v228
	v_lshl_add_u64 v[198:199], v[180:181], 0, v[208:209]
	v_lshlrev_b32_e32 v208, 7, v52
	v_lshl_add_u64 v[204:205], v[180:181], 0, v[208:209]
	v_mul_u32_u24_e32 v208, 0x140, v52
	v_or_b32_e32 v52, s6, v229
	v_lshl_add_u64 v[206:207], v[184:185], 0, v[208:209]
	v_mul_u32_u24_e32 v208, 0x140, v52
	v_or_b32_e32 v53, s6, v230
	v_lshl_add_u64 v[216:217], v[184:185], 0, v[208:209]
	v_lshlrev_b32_e32 v208, 7, v53
	v_lshl_add_u64 v[218:219], v[180:181], 0, v[208:209]
	v_mul_u32_u24_e32 v208, 0x140, v53
	v_add_lshl_u32 v196, s6, v165, 7
	s_movk_i32 s4, 0x140
	v_lshl_add_u64 v[220:221], v[184:185], 0, v[208:209]
	v_lshlrev_b32_e32 v208, 7, v52
	v_lshl_add_u64 v[200:201], v[182:183], 0, v[196:197]
	v_mad_u64_u32 v[202:203], s[4:5], v58, s4, v[184:185]
	v_lshl_add_u64 v[222:223], v[180:181], 0, v[208:209]
	v_mov_b32_e32 v210, 0
	global_load_dword v211, v210, s[74:75]
	global_load_dword v211, v210, s[74:75]
.LBB0_454:
	s_waitcnt vmcnt(13)
	v_mfma_f32_16x16x32_bf16 v[52:55], v[76:79], v[0:3], 0
	v_ashrrev_i32_e32 v191, 31, v190
	v_lshlrev_b64 v[116:117], 2, v[190:191]
	v_lshl_add_u64 v[64:65], s[44:45], 0, v[116:117]
	s_waitcnt vmcnt(12)
	v_mfma_f32_16x16x32_bf16 v[118:121], v[80:83], v[8:11], v[52:55]
	v_lshl_add_u64 v[224:225], s[74:75], 0, v[194:195]
	s_mov_b32 s6, 0x30f00000
	v_or_b32_e32 v138, 0x400, v196
	s_waitcnt vmcnt(7)
	v_mfma_f32_16x16x32_bf16 v[52:55], v[88:91], v[0:3], 0
	v_mov_b32_e32 v139, v197
	s_nop 1
	v_add_f32_e32 v96, v96, v118
	v_add_f32_e32 v97, v97, v119
	s_waitcnt vmcnt(6)
	v_mfma_f32_16x16x32_bf16 v[122:125], v[92:95], v[8:11], v[52:55]
	v_lshl_add_u64 v[92:93], s[74:75], 0, v[204:205]
	v_add_f32_e32 v98, v98, v120
	v_add_f32_e32 v99, v99, v121
	s_waitcnt vmcnt(5)
	v_mfma_f32_16x16x32_bf16 v[52:55], v[100:103], v[0:3], 0
	v_mul_f32_e32 v96, 0xbfb8aa3b, v96
	s_nop 1
	v_add_f32_e32 v84, v84, v122
	v_add_f32_e32 v85, v85, v123
	s_waitcnt vmcnt(4)
	v_mfma_f32_16x16x32_bf16 v[126:129], v[104:107], v[8:11], v[52:55]
	v_lshl_add_u64 v[104:105], s[74:75], 0, v[218:219]
	v_mul_f32_e32 v97, 0xbfb8aa3b, v97
	v_mul_f32_e32 v98, 0xbfb8aa3b, v98
	s_waitcnt vmcnt(3)
	v_mfma_f32_16x16x32_bf16 v[52:55], v[108:111], v[0:3], 0
	v_mul_f32_e32 v99, 0xbfb8aa3b, v99
	s_nop 1
	v_add_f32_e32 v72, v72, v126
	v_add_f32_e32 v73, v73, v127
	s_waitcnt vmcnt(2)
	v_mfma_f32_16x16x32_bf16 v[130:133], v[112:115], v[8:11], v[52:55]
	v_lshl_add_u64 v[112:113], s[74:75], 0, v[222:223]
	v_add_f32_e32 v74, v74, v128
	v_add_f32_e32 v75, v75, v129
	v_lshl_add_u64 v[52:53], s[74:75], 0, v[198:199]
	global_load_dwordx4 v[76:79], v[52:53], off
	global_load_dwordx4 v[80:83], v[52:53], off offset:64
	s_nop 0
	global_load_dwordx4 v[52:55], v[64:65], off offset:48
	global_load_dwordx4 v[56:59], v[64:65], off offset:32
	global_load_dwordx4 v[60:63], v[64:65], off offset:16
	s_nop 0
	global_load_dwordx4 v[64:67], v[64:65], off
	s_nop 0
	global_load_dwordx4 v[88:91], v[92:93], off
	s_nop 0
	global_load_dwordx4 v[92:95], v[92:93], off offset:64
	s_nop 0
	global_load_dwordx4 v[100:103], v[104:105], off
	s_nop 0
	global_load_dwordx4 v[104:107], v[104:105], off offset:64
	s_nop 0
	global_load_dwordx4 v[108:111], v[112:113], off
	s_nop 0
	global_load_dwordx4 v[112:115], v[112:113], off offset:64
	v_add_f32_e32 v68, v68, v130
	v_add_f32_e32 v69, v69, v131
	v_add_f32_e32 v70, v70, v132
	v_add_f32_e32 v71, v71, v133
	v_mul_f32_e32 v72, 0xbfb8aa3b, v72
	v_mul_f32_e32 v73, 0xbfb8aa3b, v73
	v_mul_f32_e32 v74, 0xbfb8aa3b, v74
	v_mul_f32_e32 v75, 0xbfb8aa3b, v75
	v_mul_f32_e32 v68, 0xbfb8aa3b, v68
	v_mul_f32_e32 v69, 0xbfb8aa3b, v69
	v_mul_f32_e32 v70, 0xbfb8aa3b, v70
	v_mul_f32_e32 v71, 0xbfb8aa3b, v71
	v_exp_f32_e32 v72, v72
	v_exp_f32_e32 v73, v73
	v_exp_f32_e32 v74, v74
	v_exp_f32_e32 v75, v75
	v_exp_f32_e32 v68, v68
	v_exp_f32_e32 v69, v69
	v_exp_f32_e32 v70, v70
	v_exp_f32_e32 v71, v71
	v_mul_f32_e32 v84, 0xbfb8aa3b, v84
	v_mul_f32_e32 v85, 0xbfb8aa3b, v85
	v_add_f32_e32 v86, v86, v124
	v_add_f32_e32 v87, v87, v125
	v_exp_f32_e32 v96, v96
	v_exp_f32_e32 v97, v97
	v_exp_f32_e32 v98, v98
	v_exp_f32_e32 v99, v99
	v_exp_f32_e32 v84, v84
	v_exp_f32_e32 v85, v85
	v_mul_f32_e32 v86, 0xbfb8aa3b, v86
	v_mul_f32_e32 v87, 0xbfb8aa3b, v87
	v_exp_f32_e32 v86, v86
	v_exp_f32_e32 v87, v87
	v_add_f32_e32 v72, 1.0, v72
	v_add_f32_e32 v73, 1.0, v73
	v_add_f32_e32 v74, 1.0, v74
	v_add_f32_e32 v75, 1.0, v75
	v_add_f32_e32 v68, 1.0, v68
	v_add_f32_e32 v69, 1.0, v69
	v_add_f32_e32 v70, 1.0, v70
	v_add_f32_e32 v71, 1.0, v71
	v_rcp_f32_e32 v72, v72
	v_rcp_f32_e32 v73, v73
	v_rcp_f32_e32 v74, v74
	v_rcp_f32_e32 v75, v75
	v_rcp_f32_e32 v68, v68
	v_rcp_f32_e32 v69, v69
	v_rcp_f32_e32 v70, v70
	v_rcp_f32_e32 v71, v71
	v_add_f32_e32 v96, 1.0, v96
	v_add_f32_e32 v97, 1.0, v97
	v_add_f32_e32 v98, 1.0, v98
	v_add_f32_e32 v99, 1.0, v99
	v_add_f32_e32 v84, 1.0, v84
	v_add_f32_e32 v85, 1.0, v85
	v_rcp_f32_e32 v96, v96
	v_rcp_f32_e32 v97, v97
	v_rcp_f32_e32 v98, v98
	v_rcp_f32_e32 v99, v99
	v_rcp_f32_e32 v84, v84
	v_rcp_f32_e32 v85, v85
	v_add_f32_e32 v86, 1.0, v86
	v_add_f32_e32 v87, 1.0, v87
	v_rcp_f32_e32 v86, v86
	v_rcp_f32_e32 v87, v87
	v_pk_mul_f32 v[72:73], v[72:73], s[76:77] op_sel_hi:[1,0]
	v_pk_mul_f32 v[74:75], v[74:75], s[76:77] op_sel_hi:[1,0]
	v_pk_mul_f32 v[68:69], v[68:69], s[76:77] op_sel_hi:[1,0]
	v_pk_mul_f32 v[70:71], v[70:71], s[76:77] op_sel_hi:[1,0]
	v_cvt_pk_bf16_f32 v72, v72, v73
	v_cvt_pk_bf16_f32 v73, v74, v75
	v_cvt_pk_bf16_f32 v74, v68, v69
	v_cvt_pk_bf16_f32 v75, v70, v71
	s_waitcnt vmcnt(11)
	v_mfma_f32_16x16x32_bf16 v[68:71], v[76:79], v[4:7], 0
	v_mul_f32_e64 v96, v96, s76
	v_mul_f32_e64 v97, v97, s76
	v_pk_mul_f32 v[98:99], v[98:99], s[76:77] op_sel_hi:[1,0]
	v_pk_mul_f32 v[84:85], v[84:85], s[76:77] op_sel_hi:[1,0]
	v_pk_mul_f32 v[86:87], v[86:87], s[76:77] op_sel_hi:[1,0]
	v_cvt_pk_bf16_f32 v96, v96, v97
	v_cvt_pk_bf16_f32 v97, v98, v99
	v_cvt_pk_bf16_f32 v98, v84, v85
	v_add_co_u32_e32 v84, vcc, s6, v224
	v_cvt_pk_bf16_f32 v99, v86, v87
	s_nop 0
	v_addc_co_u32_e32 v85, vcc, 0, v225, vcc
	global_store_dwordx4 v[84:85], v[96:99], off
	s_mov_b32 s6, 0x44900000
	global_store_dwordx4 v[84:85], v[72:75], off offset:16
	s_waitcnt vmcnt(12)
	v_mfma_f32_16x16x32_bf16 v[96:99], v[80:83], v[12:15], v[68:71]
	v_lshl_add_u64 v[80:81], s[48:49], 0, v[116:117]
	v_lshl_add_u64 v[126:127], v[168:169], 0, v[138:139]
	s_waitcnt vmcnt(7)
	v_mfma_f32_16x16x32_bf16 v[68:71], v[88:91], v[4:7], 0
	v_lshl_add_u64 v[88:89], s[74:75], 0, v[200:201]
	v_or_b32_e32 v90, 0x200, v196
	v_mov_b32_e32 v91, v197
	s_waitcnt vmcnt(6)
	v_mfma_f32_16x16x32_bf16 v[92:95], v[92:95], v[12:15], v[68:71]
	v_lshl_add_u64 v[118:119], v[168:169], 0, v[90:91]
	v_or_b32_e32 v140, 0x600, v196
	v_mov_b32_e32 v141, v197
	s_waitcnt vmcnt(5)
	v_mfma_f32_16x16x32_bf16 v[68:71], v[100:103], v[4:7], 0
	v_lshl_add_u64 v[134:135], v[168:169], 0, v[140:141]
	s_nop 1
	v_add_f32_e32 v60, v60, v92
	v_add_f32_e32 v61, v61, v93
	s_waitcnt vmcnt(4)
	v_mfma_f32_16x16x32_bf16 v[100:103], v[104:107], v[12:15], v[68:71]
	v_add_f32_e32 v64, v64, v96
	v_add_f32_e32 v65, v65, v97
	v_add_f32_e32 v66, v66, v98
	s_waitcnt vmcnt(3)
	v_mfma_f32_16x16x32_bf16 v[68:71], v[108:111], v[4:7], 0
	v_add_f32_e32 v67, v67, v99
	s_nop 1
	v_add_f32_e32 v56, v56, v100
	v_mul_f32_e32 v56, 0xbfb8aa3b, v56
	s_waitcnt vmcnt(2)
	v_mfma_f32_16x16x32_bf16 v[84:87], v[112:115], v[12:15], v[68:71]
	v_exp_f32_e32 v56, v56
	v_add_f32_e32 v62, v62, v94
	v_add_f32_e32 v63, v63, v95
	v_add_co_u32_e32 v68, vcc, s6, v88
	v_add_f32_e32 v56, 1.0, v56
	s_nop 0
	v_addc_co_u32_e32 v69, vcc, 0, v89, vcc
	global_load_dwordx4 v[104:107], v[68:69], off
	global_load_dwordx4 v[108:111], v[68:69], off offset:64
	s_nop 0
	global_load_dwordx4 v[68:71], v[80:81], off offset:48
	global_load_dwordx4 v[72:75], v[80:81], off offset:32
	global_load_dwordx4 v[76:79], v[80:81], off offset:16
	s_nop 0
	global_load_dwordx4 v[80:83], v[80:81], off
	s_nop 0
	global_load_dwordx4 v[112:115], v[118:119], off
	s_nop 0
	global_load_dwordx4 v[118:121], v[118:119], off offset:64
	s_nop 0
	global_load_dwordx4 v[122:125], v[126:127], off
	s_nop 0
	global_load_dwordx4 v[126:129], v[126:127], off offset:64
	s_nop 0
	global_load_dwordx4 v[130:133], v[134:135], off
	s_nop 0
	global_load_dwordx4 v[134:137], v[134:135], off offset:64
	v_add_f32_e32 v52, v52, v84
	v_mul_f32_e32 v52, 0xbfb8aa3b, v52
	v_exp_f32_e32 v52, v52
	v_rcp_f32_e32 v92, v56
	v_add_f32_e32 v56, v57, v101
	v_mul_f32_e32 v56, 0xbfb8aa3b, v56
	v_add_f32_e32 v52, 1.0, v52
	v_rcp_f32_e32 v84, v52
	v_add_f32_e32 v52, v53, v85
	v_mul_f32_e32 v52, 0xbfb8aa3b, v52
	v_exp_f32_e32 v56, v56
	v_exp_f32_e32 v52, v52
	v_mul_f32_e32 v64, 0xbfb8aa3b, v64
	v_mul_f32_e32 v65, 0xbfb8aa3b, v65
	v_add_f32_e32 v56, 1.0, v56
	v_add_f32_e32 v52, 1.0, v52
	v_rcp_f32_e32 v93, v56
	v_add_f32_e32 v56, v58, v102
	v_rcp_f32_e32 v85, v52
	v_add_f32_e32 v52, v54, v86
	v_mul_f32_e32 v56, 0xbfb8aa3b, v56
	v_mul_f32_e32 v52, 0xbfb8aa3b, v52
	v_exp_f32_e32 v56, v56
	v_exp_f32_e32 v52, v52
	v_mul_f32_e32 v66, 0xbfb8aa3b, v66
	v_mul_f32_e32 v67, 0xbfb8aa3b, v67
	v_add_f32_e32 v56, 1.0, v56
	v_add_f32_e32 v52, 1.0, v52
	v_mul_f32_e32 v60, 0xbfb8aa3b, v60
	v_mul_f32_e32 v61, 0xbfb8aa3b, v61
	v_mul_f32_e32 v62, 0xbfb8aa3b, v62
	v_mul_f32_e32 v63, 0xbfb8aa3b, v63
	v_rcp_f32_e32 v58, v56
	v_add_f32_e32 v56, v59, v103
	v_rcp_f32_e32 v86, v52
	v_add_f32_e32 v52, v55, v87
	v_exp_f32_e32 v64, v64
	v_exp_f32_e32 v65, v65
	v_exp_f32_e32 v66, v66
	v_exp_f32_e32 v67, v67
	v_exp_f32_e32 v60, v60
	v_exp_f32_e32 v61, v61
	v_exp_f32_e32 v62, v62
	v_exp_f32_e32 v63, v63
	v_mul_f32_e32 v56, 0xbfb8aa3b, v56
	v_mul_f32_e32 v52, 0xbfb8aa3b, v52
	v_exp_f32_e32 v56, v56
	v_exp_f32_e32 v52, v52
	v_add_f32_e32 v64, 1.0, v64
	v_add_f32_e32 v65, 1.0, v65
	v_add_f32_e32 v66, 1.0, v66
	v_add_f32_e32 v67, 1.0, v67
	v_add_f32_e32 v60, 1.0, v60
	v_add_f32_e32 v61, 1.0, v61
	v_add_f32_e32 v62, 1.0, v62
	v_add_f32_e32 v63, 1.0, v63
	v_rcp_f32_e32 v64, v64
	v_rcp_f32_e32 v65, v65
	v_rcp_f32_e32 v66, v66
	v_rcp_f32_e32 v67, v67
	v_rcp_f32_e32 v60, v60
	v_rcp_f32_e32 v61, v61
	v_rcp_f32_e32 v62, v62
	v_rcp_f32_e32 v63, v63
	v_add_f32_e32 v56, 1.0, v56
	v_add_f32_e32 v52, 1.0, v52
	v_rcp_f32_e32 v59, v56
	v_rcp_f32_e32 v87, v52
	v_add_co_u32_e32 v56, vcc, s97, v224
	v_cvt_pk_bf16_f32 v52, v64, v65
	v_cvt_pk_bf16_f32 v53, v66, v67
	v_cvt_pk_bf16_f32 v54, v60, v61
	v_cvt_pk_bf16_f32 v55, v62, v63
	v_addc_co_u32_e32 v57, vcc, 0, v225, vcc
	global_store_dwordx4 v[56:57], v[52:55], off
	s_mov_b32 s6, 0x44a00000
	v_lshl_add_u64 v[64:65], s[50:51], 0, v[116:117]
	v_cvt_pk_bf16_f32 v52, v92, v93
	v_cvt_pk_bf16_f32 v53, v58, v59
	v_cvt_pk_bf16_f32 v54, v84, v85
	v_cvt_pk_bf16_f32 v55, v86, v87
	global_store_dwordx4 v[56:57], v[52:55], off offset:16
	v_lshl_add_u64 v[160:161], s[74:75], 0, v[216:217]
	s_add_i32 s4, s10, 1
	s_waitcnt vmcnt(13)
	v_mfma_f32_16x16x32_bf16 v[52:55], v[104:107], v[16:19], 0
	s_cmp_lt_u32 s4, s60
	s_cselect_b32 s5, s4, s10
	s_lshl_b32 s5, s5, 6
	s_waitcnt vmcnt(12)
	v_mfma_f32_16x16x32_bf16 v[84:87], v[108:111], v[24:27], v[52:55]
	s_add_i32 s5, s5, s2
	s_cmp_ge_u32 s4, s60
	v_lshl_add_u64 v[194:195], v[194:195], 0, s[34:35]
	s_waitcnt vmcnt(7)
	v_mfma_f32_16x16x32_bf16 v[52:55], v[112:115], v[16:19], 0
	v_lshl_add_u64 v[112:113], v[170:171], 0, v[90:91]
	s_nop 1
	v_add_f32_e32 v80, v80, v84
	v_add_f32_e32 v81, v81, v85
	s_waitcnt vmcnt(6)
	v_mfma_f32_16x16x32_bf16 v[92:95], v[118:121], v[24:27], v[52:55]
	v_lshl_add_u64 v[120:121], v[170:171], 0, v[138:139]
	v_add_f32_e32 v82, v82, v86
	v_add_f32_e32 v83, v83, v87
	s_waitcnt vmcnt(5)
	v_mfma_f32_16x16x32_bf16 v[52:55], v[122:125], v[16:19], 0
	v_mul_f32_e32 v80, 0xbfb8aa3b, v80
	s_nop 1
	v_add_f32_e32 v76, v76, v92
	v_add_f32_e32 v77, v77, v93
	s_waitcnt vmcnt(4)
	v_mfma_f32_16x16x32_bf16 v[96:99], v[126:129], v[24:27], v[52:55]
	v_lshl_add_u64 v[128:129], v[170:171], 0, v[140:141]
	v_mul_f32_e32 v76, 0xbfb8aa3b, v76
	v_mul_f32_e32 v77, 0xbfb8aa3b, v77
	s_waitcnt vmcnt(3)
	v_mfma_f32_16x16x32_bf16 v[52:55], v[130:133], v[16:19], 0
	v_add_f32_e32 v78, v78, v94
	v_add_f32_e32 v79, v79, v95
	v_mul_f32_e32 v81, 0xbfb8aa3b, v81
	s_waitcnt vmcnt(2)
	v_mfma_f32_16x16x32_bf16 v[100:103], v[134:137], v[24:27], v[52:55]
	v_mul_f32_e32 v82, 0xbfb8aa3b, v82
	v_mul_f32_e32 v83, 0xbfb8aa3b, v83
	v_exp_f32_e32 v76, v76
	v_add_co_u32_e32 v52, vcc, s6, v88
	v_exp_f32_e32 v77, v77
	s_nop 0
	v_addc_co_u32_e32 v53, vcc, 0, v89, vcc
	global_load_dwordx4 v[104:107], v[52:53], off
	global_load_dwordx4 v[108:111], v[52:53], off offset:64
	s_nop 0
	global_load_dwordx4 v[52:55], v[64:65], off offset:48
	global_load_dwordx4 v[56:59], v[64:65], off offset:32
	global_load_dwordx4 v[60:63], v[64:65], off offset:16
	s_nop 0
	global_load_dwordx4 v[64:67], v[64:65], off
	s_nop 0
	global_load_dwordx4 v[88:91], v[112:113], off
	s_nop 0
	global_load_dwordx4 v[112:115], v[112:113], off offset:64
	s_nop 0
	global_load_dwordx4 v[116:119], v[120:121], off
	s_nop 0
	global_load_dwordx4 v[120:123], v[120:121], off offset:64
	s_nop 0
	global_load_dwordx4 v[124:127], v[128:129], off
	s_nop 0
	global_load_dwordx4 v[128:131], v[128:129], off offset:64
	v_add_f32_e32 v68, v68, v100
	v_add_f32_e32 v69, v69, v101
	v_mul_f32_e32 v68, 0xbfb8aa3b, v68
	v_mul_f32_e32 v69, 0xbfb8aa3b, v69
	v_exp_f32_e32 v68, v68
	v_exp_f32_e32 v69, v69
	v_mul_f32_e32 v78, 0xbfb8aa3b, v78
	v_mul_f32_e32 v79, 0xbfb8aa3b, v79
	v_add_f32_e32 v68, 1.0, v68
	v_add_f32_e32 v69, 1.0, v69
	v_rcp_f32_e32 v68, v68
	v_rcp_f32_e32 v69, v69
	v_add_f32_e32 v72, v72, v96
	v_add_f32_e32 v73, v73, v97
	v_add_f32_e32 v74, v74, v98
	v_add_f32_e32 v75, v75, v99
	v_pk_mul_f32 v[84:85], v[68:69], s[76:77] op_sel_hi:[1,0]
	v_add_f32_e32 v68, v70, v102
	v_add_f32_e32 v69, v71, v103
	v_exp_f32_e32 v80, v80
	v_exp_f32_e32 v81, v81
	v_exp_f32_e32 v82, v82
	v_exp_f32_e32 v83, v83
	v_exp_f32_e32 v78, v78
	v_exp_f32_e32 v79, v79
	v_mul_f32_e32 v72, 0xbfb8aa3b, v72
	v_mul_f32_e32 v73, 0xbfb8aa3b, v73
	v_mul_f32_e32 v74, 0xbfb8aa3b, v74
	v_mul_f32_e32 v75, 0xbfb8aa3b, v75
	v_mul_f32_e32 v68, 0xbfb8aa3b, v68
	v_mul_f32_e32 v69, 0xbfb8aa3b, v69
	v_exp_f32_e32 v72, v72
	v_exp_f32_e32 v73, v73
	v_exp_f32_e32 v74, v74
	v_exp_f32_e32 v75, v75
	v_exp_f32_e32 v68, v68
	v_exp_f32_e32 v69, v69
	v_add_f32_e32 v76, 1.0, v76
	v_add_f32_e32 v77, 1.0, v77
	v_add_f32_e32 v80, 1.0, v80
	v_add_f32_e32 v81, 1.0, v81
	v_add_f32_e32 v82, 1.0, v82
	v_add_f32_e32 v83, 1.0, v83
	v_rcp_f32_e32 v76, v76
	v_rcp_f32_e32 v77, v77
	v_add_f32_e32 v78, 1.0, v78
	v_add_f32_e32 v79, 1.0, v79
	v_rcp_f32_e32 v80, v80
	v_rcp_f32_e32 v81, v81
	v_rcp_f32_e32 v82, v82
	v_rcp_f32_e32 v83, v83
	v_rcp_f32_e32 v78, v78
	v_rcp_f32_e32 v79, v79
	v_add_f32_e32 v72, 1.0, v72
	v_add_f32_e32 v73, 1.0, v73
	v_add_f32_e32 v74, 1.0, v74
	v_add_f32_e32 v75, 1.0, v75
	v_add_f32_e32 v68, 1.0, v68
	v_add_f32_e32 v69, 1.0, v69
	v_rcp_f32_e32 v72, v72
	v_rcp_f32_e32 v73, v73
	v_rcp_f32_e32 v74, v74
	v_rcp_f32_e32 v75, v75
	v_rcp_f32_e32 v68, v68
	v_rcp_f32_e32 v69, v69
	v_pk_mul_f32 v[76:77], v[76:77], s[76:77] op_sel_hi:[1,0]
	s_mov_b32 s6, 0x33000000
	v_pk_mul_f32 v[80:81], v[80:81], s[76:77] op_sel_hi:[1,0]
	v_pk_mul_f32 v[82:83], v[82:83], s[76:77] op_sel_hi:[1,0]
	v_pk_mul_f32 v[78:79], v[78:79], s[76:77] op_sel_hi:[1,0]
	v_cvt_pk_bf16_f32 v70, v76, v77
	v_add_co_u32_e32 v76, vcc, s6, v224
	v_pk_mul_f32 v[72:73], v[72:73], s[76:77] op_sel_hi:[1,0]
	v_pk_mul_f32 v[74:75], v[74:75], s[76:77] op_sel_hi:[1,0]
	v_pk_mul_f32 v[86:87], v[68:69], s[76:77] op_sel_hi:[1,0]
	v_cvt_pk_bf16_f32 v68, v80, v81
	v_cvt_pk_bf16_f32 v69, v82, v83
	v_cvt_pk_bf16_f32 v71, v78, v79
	v_addc_co_u32_e32 v77, vcc, 0, v225, vcc
	global_store_dwordx4 v[76:77], v[68:71], off
	v_lshl_add_u64 v[100:101], s[74:75], 0, v[202:203]
	v_lshl_add_u64 v[140:141], s[74:75], 0, v[220:221]
	v_cvt_pk_bf16_f32 v68, v72, v73
	v_cvt_pk_bf16_f32 v69, v74, v75
	v_cvt_pk_bf16_f32 v70, v84, v85
	v_cvt_pk_bf16_f32 v71, v86, v87
	global_store_dwordx4 v[76:77], v[68:71], off offset:16
	v_lshl_add_u64 v[196:197], v[196:197], 0, s[18:19]
	v_lshl_add_u64 v[198:199], v[198:199], 0, s[18:19]
	s_waitcnt vmcnt(13)
	v_mfma_f32_16x16x32_bf16 v[68:71], v[104:107], v[20:23], 0
	v_lshl_add_u64 v[200:201], v[200:201], 0, s[18:19]
	v_lshl_add_u64 v[202:203], v[202:203], 0, s[22:23]
	v_lshl_add_u64 v[204:205], v[204:205], 0, s[18:19]
	s_waitcnt vmcnt(12)
	v_mfma_f32_16x16x32_bf16 v[80:83], v[108:111], v[28:31], v[68:71]
	v_lshl_add_u64 v[216:217], v[216:217], 0, s[22:23]
	v_lshl_add_u64 v[218:219], v[218:219], 0, s[18:19]
	v_lshl_add_u64 v[220:221], v[220:221], 0, s[22:23]
	s_waitcnt vmcnt(7)
	v_mfma_f32_16x16x32_bf16 v[68:71], v[88:91], v[20:23], 0
	global_load_dwordx4 v[84:87], v[100:101], off offset:-128
	global_load_dwordx4 v[88:91], v[100:101], off offset:-64
	global_load_dwordx4 v[92:95], v[100:101], off
	global_load_dwordx4 v[96:99], v[100:101], off offset:64
	s_nop 0
	global_load_dwordx4 v[100:103], v[100:101], off offset:128
	v_add_f32_e32 v64, v64, v80
	v_add_f32_e32 v65, v65, v81
	s_waitcnt vmcnt(11)
	v_mfma_f32_16x16x32_bf16 v[76:79], v[112:115], v[28:31], v[68:71]
	v_add_f32_e32 v66, v66, v82
	v_add_f32_e32 v67, v67, v83
	v_mul_f32_e32 v64, 0xbfb8aa3b, v64
	s_waitcnt vmcnt(10)
	v_mfma_f32_16x16x32_bf16 v[68:71], v[116:119], v[20:23], 0
	v_mul_f32_e32 v65, 0xbfb8aa3b, v65
	s_nop 1
	v_add_f32_e32 v60, v60, v76
	v_add_f32_e32 v61, v61, v77
	s_waitcnt vmcnt(9)
	v_mfma_f32_16x16x32_bf16 v[72:75], v[120:123], v[28:31], v[68:71]
	v_lshl_add_u64 v[120:121], s[74:75], 0, v[206:207]
	global_load_dwordx4 v[104:107], v[120:121], off offset:-128
	global_load_dwordx4 v[108:111], v[120:121], off offset:-64
	global_load_dwordx4 v[112:115], v[120:121], off
	global_load_dwordx4 v[116:119], v[120:121], off offset:64
	s_nop 0
	global_load_dwordx4 v[120:123], v[120:121], off offset:128
	v_mul_f32_e32 v60, 0xbfb8aa3b, v60
	s_waitcnt vmcnt(13)
	v_mfma_f32_16x16x32_bf16 v[68:71], v[124:127], v[20:23], 0
	v_mul_f32_e32 v61, 0xbfb8aa3b, v61
	v_add_f32_e32 v62, v62, v78
	v_add_f32_e32 v63, v63, v79
	s_waitcnt vmcnt(12)
	v_mfma_f32_16x16x32_bf16 v[68:71], v[128:131], v[28:31], v[68:71]
	v_mul_f32_e32 v66, 0xbfb8aa3b, v66
	v_mul_f32_e32 v67, 0xbfb8aa3b, v67
	v_exp_f32_e32 v60, v60
	v_exp_f32_e32 v61, v61
	v_mul_f32_e32 v62, 0xbfb8aa3b, v62
	s_nop 2
	v_add_f32_e32 v52, v52, v68
	v_mul_f32_e32 v52, 0xbfb8aa3b, v52
	v_exp_f32_e32 v52, v52
	v_mul_f32_e32 v63, 0xbfb8aa3b, v63
	v_add_f32_e32 v56, v56, v72
	v_add_f32_e32 v57, v57, v73
	v_add_f32_e32 v52, 1.0, v52
	v_rcp_f32_e32 v68, v52
	v_add_f32_e32 v52, v53, v69
	v_mul_f32_e32 v52, 0xbfb8aa3b, v52
	v_exp_f32_e32 v52, v52
	v_add_f32_e32 v58, v58, v74
	v_add_f32_e32 v59, v59, v75
	v_exp_f32_e32 v64, v64
	v_add_f32_e32 v52, 1.0, v52
	v_rcp_f32_e32 v69, v52
	v_add_f32_e32 v52, v54, v70
	v_mul_f32_e32 v52, 0xbfb8aa3b, v52
	v_exp_f32_e32 v52, v52
	v_exp_f32_e32 v65, v65
	v_exp_f32_e32 v66, v66
	v_exp_f32_e32 v67, v67
	v_add_f32_e32 v52, 1.0, v52
	v_rcp_f32_e32 v70, v52
	v_add_f32_e32 v52, v55, v71
	v_exp_f32_e32 v62, v62
	v_exp_f32_e32 v63, v63
	v_mul_f32_e32 v56, 0xbfb8aa3b, v56
	v_mul_f32_e32 v57, 0xbfb8aa3b, v57
	v_mul_f32_e32 v58, 0xbfb8aa3b, v58
	v_mul_f32_e32 v59, 0xbfb8aa3b, v59
	v_mul_f32_e32 v52, 0xbfb8aa3b, v52
	v_exp_f32_e32 v56, v56
	v_exp_f32_e32 v57, v57
	v_exp_f32_e32 v58, v58
	v_exp_f32_e32 v59, v59
	v_exp_f32_e32 v52, v52
	v_add_f32_e32 v60, 1.0, v60
	v_add_f32_e32 v61, 1.0, v61
	v_add_f32_e32 v64, 1.0, v64
	v_add_f32_e32 v65, 1.0, v65
	v_add_f32_e32 v66, 1.0, v66
	v_add_f32_e32 v67, 1.0, v67
	v_rcp_f32_e32 v60, v60
	v_rcp_f32_e32 v61, v61
	v_add_f32_e32 v62, 1.0, v62
	v_add_f32_e32 v63, 1.0, v63
	v_rcp_f32_e32 v64, v64
	v_rcp_f32_e32 v65, v65
	v_rcp_f32_e32 v66, v66
	v_rcp_f32_e32 v67, v67
	v_rcp_f32_e32 v62, v62
	v_rcp_f32_e32 v63, v63
	v_add_f32_e32 v56, 1.0, v56
	v_add_f32_e32 v57, 1.0, v57
	v_add_f32_e32 v58, 1.0, v58
	v_add_f32_e32 v59, 1.0, v59
	v_add_f32_e32 v52, 1.0, v52
	v_rcp_f32_e32 v56, v56
	v_rcp_f32_e32 v57, v57
	v_rcp_f32_e32 v58, v58
	v_rcp_f32_e32 v59, v59
	v_rcp_f32_e32 v71, v52
	v_cvt_pk_bf16_f32 v54, v60, v61
	v_add_co_u32_e32 v60, vcc, s70, v224
	v_cvt_pk_bf16_f32 v52, v64, v65
	v_cvt_pk_bf16_f32 v53, v66, v67
	v_cvt_pk_bf16_f32 v55, v62, v63
	v_addc_co_u32_e32 v61, vcc, 0, v225, vcc
	global_load_dwordx4 v[124:127], v[140:141], off offset:-128
	global_load_dwordx4 v[128:131], v[140:141], off offset:-64
	global_load_dwordx4 v[132:135], v[140:141], off
	global_load_dwordx4 v[136:139], v[140:141], off offset:64
	s_nop 0
	global_load_dwordx4 v[140:143], v[140:141], off offset:128
	s_nop 0
	global_load_dwordx4 v[144:147], v[160:161], off offset:-128
	global_load_dwordx4 v[148:151], v[160:161], off offset:-64
	global_load_dwordx4 v[152:155], v[160:161], off
	global_load_dwordx4 v[156:159], v[160:161], off offset:64
	s_nop 0
	global_load_dwordx4 v[160:163], v[160:161], off offset:128
	global_store_dwordx4 v[60:61], v[52:55], off
	s_waitcnt vmcnt(5)
	v_mfma_f32_16x16x32_bf16 v[64:67], v[144:147], v[32:35], 0
	v_cvt_pk_bf16_f32 v52, v56, v57
	v_cvt_pk_bf16_f32 v53, v58, v59
	v_cvt_pk_bf16_f32 v54, v68, v69
	v_cvt_pk_bf16_f32 v55, v70, v71
	global_store_dwordx4 v[60:61], v[52:55], off offset:16
	v_mfma_f32_16x16x32_bf16 v[56:59], v[104:107], v[32:35], 0
	v_or_b32_e32 v68, s5, v227
	v_add_u32_e32 v70, s5, v164
	v_ashrrev_i32_e32 v69, 31, v68
	v_mfma_f32_16x16x32_bf16 v[52:55], v[84:87], v[32:35], 0
	v_ashrrev_i32_e32 v71, 31, v70
	v_lshlrev_b64 v[68:69], 7, v[68:69]
	v_mfma_f32_16x16x32_bf16 v[52:55], v[88:91], v[36:39], v[52:55]
	v_lshl_add_u64 v[88:89], v[70:71], 2, s[42:43]
	v_lshl_add_u64 v[206:207], v[206:207], 0, s[22:23]
	v_lshl_add_u64 v[222:223], v[222:223], 0, s[18:19]
	v_mfma_f32_16x16x32_bf16 v[52:55], v[92:95], v[40:43], v[52:55]
	s_mov_b32 s10, s4
	v_mfma_f32_16x16x32_bf16 v[56:59], v[108:111], v[36:39], v[56:59]
	v_mfma_f32_16x16x32_bf16 v[52:55], v[96:99], v[44:47], v[52:55]
	v_mfma_f32_16x16x32_bf16 v[56:59], v[112:115], v[40:43], v[56:59]
	v_lshl_add_u64 v[112:113], v[168:169], 0, v[68:69]
	v_mfma_f32_16x16x32_bf16 v[52:55], v[100:103], v[48:51], v[52:55]
	global_load_dwordx4 v[76:79], v[112:113], off
	global_load_dwordx4 v[80:83], v[112:113], off offset:64
	global_load_dwordx4 v[68:71], v[88:89], off offset:48
	global_load_dwordx4 v[72:75], v[88:89], off offset:32
	global_load_dwordx4 v[84:87], v[88:89], off offset:16
	global_load_dwordx4 v[96:99], v[88:89], off
	s_nop 0
	global_load_dwordx4 v[88:91], v[112:113], off offset:512
	global_load_dwordx4 v[92:95], v[112:113], off offset:576
	global_load_dwordx4 v[100:103], v[112:113], off offset:1024
	global_load_dwordx4 v[104:107], v[112:113], off offset:1088
	global_load_dwordx4 v[108:111], v[112:113], off offset:1536
	s_nop 0
	global_load_dwordx4 v[112:115], v[112:113], off offset:1600
	v_cvt_pk_bf16_f32 v52, v52, v53
	v_mfma_f32_16x16x32_bf16 v[60:63], v[124:127], v[32:35], 0
	v_cvt_pk_bf16_f32 v53, v54, v55
	v_mfma_f32_16x16x32_bf16 v[60:63], v[128:131], v[36:39], v[60:63]
	s_waitcnt vmcnt(17)
	v_mfma_f32_16x16x32_bf16 v[64:67], v[148:151], v[36:39], v[64:67]
	v_mfma_f32_16x16x32_bf16 v[60:63], v[132:135], v[40:43], v[60:63]
	s_waitcnt vmcnt(16)
	v_mfma_f32_16x16x32_bf16 v[64:67], v[152:155], v[40:43], v[64:67]
	v_mfma_f32_16x16x32_bf16 v[56:59], v[116:119], v[44:47], v[56:59]
	v_lshl_add_u64 v[116:117], v[190:191], 1, v[192:193]
	v_add_u32_e32 v190, 64, v190
	v_mfma_f32_16x16x32_bf16 v[60:63], v[136:139], v[44:47], v[60:63]
	s_waitcnt vmcnt(15)
	v_mfma_f32_16x16x32_bf16 v[64:67], v[156:159], v[44:47], v[64:67]
	v_mfma_f32_16x16x32_bf16 v[56:59], v[120:123], v[48:51], v[56:59]
	v_mfma_f32_16x16x32_bf16 v[60:63], v[140:143], v[48:51], v[60:63]
	s_waitcnt vmcnt(14)
	v_mfma_f32_16x16x32_bf16 v[64:67], v[160:163], v[48:51], v[64:67]
	s_nop 4
	v_cvt_pk_bf16_f32 v54, v56, v57
	v_cvt_pk_bf16_f32 v55, v58, v59
	global_store_dwordx4 v[116:117], v[52:55], off
	s_nop 1
	v_cvt_pk_bf16_f32 v52, v60, v61
	v_cvt_pk_bf16_f32 v53, v62, v63
	v_cvt_pk_bf16_f32 v54, v64, v65
	v_cvt_pk_bf16_f32 v55, v66, v67
	global_store_dwordx4 v[116:117], v[52:55], off offset:16
	s_cbranch_scc0 .LBB0_454
	s_add_i32 s54, s54, s55
	s_cmpk_lg_i32 s55, 0x800
	s_cbranch_scc1 .Llora_rot_ok
	s_addk_i32 s54, 0x200
	s_cmpk_lt_i32 s54, 0x1000
	s_cbranch_scc1 .Llora_rot_ok
	s_sub_i32 s54, s54, s55
